# combination on v2: LN 2-row prefetch + K-loop LDS-DMA saddr form issued before the fragment reads + s_setprio off the barrier path + LRU counted vmcnt
# speedup vs baseline: 1.0154x; 1.0091x over previous
; #define PG8_STAGE(bufoff, gbase, voff) do { _Pragma("unroll") for (int _i = 0; _i < 2; ++_i) \
;         __builtin_amdgcn_global_load_lds((const unsigned*)((const char*)(gbase) + (voff)[_i]), (PG8_LAS unsigned*)(lds + (bufoff) + ldsw + _i * 8192), 16, 0, 0); } while (0)
; #define PG8_LDA(dst, b, h) do { _Pragma("unroll") for (int m = 0; m < 4; ++m) _Pragma("unroll") for (int k = 0; k < 2; ++k) dst[m][k] = *(const PG8_LAS bf16x8*)(lds + PG8_SA(b, h) + aoff + m * 2048 + k * 1024); } while (0)
; #define PG8_LDB(dst, b, h) do { _Pragma("unroll") for (int n = 0; n < 2; ++n) _Pragma("unroll") for (int k = 0; k < 2; ++k) dst[n][k] = *(const PG8_LAS bf16x8*)(lds + PG8_SB(b, h) + boff + n * 2048 + k * 1024); } while (0)
; #define PG8_MMA(ai, bj, At, Bt) do { __builtin_amdgcn_s_setprio(1); _Pragma("unroll") for (int m = 0; m < 4; ++m) _Pragma("unroll") for (int n = 0; n < 2; ++n) _Pragma("unroll") for (int k = 0; k < 2; ++k) \
;         acc[ai][bj][m][n] = __builtin_amdgcn_mfma_f32_16x16x32_bf16(Bt[n][k], At[m][k], acc[ai][bj][m][n], 0, 0, 0); __builtin_amdgcn_s_setprio(0); } while (0)
; #define PG8_WAIT_V(n) asm volatile("s_waitcnt vmcnt(" #n ")" ::: "memory")
; #define PG8_WAIT_L(n) asm volatile("s_waitcnt lgkmcnt(" #n ")" ::: "memory")
; #define PG8_BAR __builtin_amdgcn_s_barrier()
; #define PG8_SCHED __builtin_amdgcn_sched_barrier(0)
; template <class Epi, class Sched, bool ALIGN_EPI = false, bool SP2 = false>
; __device__ __forceinline__ void gemm_phase(PG8_LAS unsigned char* lds, const Gemm g, const Sched& S, const Epi& E) {
;     ...
;             PG8_LDB(B0, 0, 0); PG8_LDB(B1, 0, 1); PG8_SCHED; PG8_LDA(At, 0, 0); PG8_STAGE(PG8_SA(1, 1), a1 + hstep, voffA);
;             PG8_WAIT_V(8); PG8_WAIT_L(0); PG8_BAR; PG8_MMA(0, 0, At, B0); PG8_MMA(0, 1, At, B1); PG8_BAR; PG8_SCHED;
;             PG8_LDA(At, 0, 1); PG8_STAGE(PG8_SB(0, 0), b2, voffB); PG8_STAGE(PG8_SB(0, 1), b2 + hstep, voffB); PG8_STAGE(PG8_SA(0, 0), a2, voffA);
;             PG8_WAIT_V(8); PG8_WAIT_L(0); PG8_BAR; PG8_MMA(1, 0, At, B0); PG8_MMA(1, 1, At, B1); PG8_BAR; PG8_SCHED;
.LBB0_139:
	s_add_u32 s34, s30, 0xfff80080
	s_addc_u32 s35, s31, -1
	s_cmp_eq_u32 s84, 28
	s_cselect_b32 s49, s23, s35
	s_cselect_b32 s48, s80, s34
	s_cselect_b32 s35, s21, s83
	s_cselect_b32 s34, s81, s82
	s_add_i32 m0, s29, 0xc000
	s_nop 0
	global_load_lds_dwordx4 v136, s[30:31]
	s_add_i32 m0, s29, 0xe000
	s_nop 0
	global_load_lds_dwordx4 v138, s[30:31]
	ds_read_b128 v[144:147], v160
	ds_read_b128 v[164:167], v160 offset:1024
	ds_read_b128 v[172:175], v160 offset:2048
	ds_read_b128 v[176:179], v160 offset:3072
	ds_read_b128 v[180:183], v161
	ds_read_b128 v[184:187], v161 offset:1024
	ds_read_b128 v[188:191], v161 offset:2048
	ds_read_b128 v[192:195], v161 offset:3072
	ds_read_b128 v[196:199], v162
	ds_read_b128 v[200:203], v162 offset:1024
	ds_read_b128 v[204:207], v162 offset:2048
	ds_read_b128 v[208:211], v162 offset:3072
	ds_read_b128 v[212:215], v162 offset:4096
	ds_read_b128 v[216:219], v162 offset:5120
	ds_read_b128 v[220:223], v162 offset:6144
	ds_read_b128 v[224:227], v162 offset:7168
	s_waitcnt vmcnt(8)
	s_waitcnt lgkmcnt(0)
	s_setprio 1
	s_barrier
	v_mfma_f32_16x16x32_bf16 v[124:127], v[144:147], v[196:199], v[124:127]
	v_mfma_f32_16x16x32_bf16 v[120:123], v[172:175], v[196:199], v[120:123]
	v_mfma_f32_16x16x32_bf16 v[116:119], v[144:147], v[204:207], v[116:119]
	v_mfma_f32_16x16x32_bf16 v[108:111], v[172:175], v[204:207], v[108:111]
	v_mfma_f32_16x16x32_bf16 v[100:103], v[144:147], v[212:215], v[100:103]
	v_mfma_f32_16x16x32_bf16 v[92:95], v[172:175], v[212:215], v[92:95]
	v_mfma_f32_16x16x32_bf16 v[84:87], v[144:147], v[220:223], v[84:87]
	v_mfma_f32_16x16x32_bf16 v[76:79], v[172:175], v[220:223], v[76:79]
	v_mfma_f32_16x16x32_bf16 v[124:127], v[164:167], v[200:203], v[124:127]
	v_mfma_f32_16x16x32_bf16 v[120:123], v[176:179], v[200:203], v[120:123]
	v_mfma_f32_16x16x32_bf16 v[116:119], v[164:167], v[208:211], v[116:119]
	v_mfma_f32_16x16x32_bf16 v[108:111], v[176:179], v[208:211], v[108:111]
	v_mfma_f32_16x16x32_bf16 v[100:103], v[164:167], v[216:219], v[100:103]
	v_mfma_f32_16x16x32_bf16 v[92:95], v[176:179], v[216:219], v[92:95]
	v_mfma_f32_16x16x32_bf16 v[84:87], v[164:167], v[224:227], v[84:87]
	v_mfma_f32_16x16x32_bf16 v[76:79], v[176:179], v[224:227], v[76:79]
	s_setprio 0
	s_setprio 1
	v_mfma_f32_16x16x32_bf16 v[112:115], v[180:183], v[196:199], v[112:115]
	v_mfma_f32_16x16x32_bf16 v[104:107], v[188:191], v[196:199], v[104:107]
	v_mfma_f32_16x16x32_bf16 v[96:99], v[180:183], v[204:207], v[96:99]
	v_mfma_f32_16x16x32_bf16 v[88:91], v[188:191], v[204:207], v[88:91]
	v_mfma_f32_16x16x32_bf16 v[80:83], v[180:183], v[212:215], v[80:83]
	v_mfma_f32_16x16x32_bf16 v[72:75], v[188:191], v[212:215], v[72:75]
	v_mfma_f32_16x16x32_bf16 v[68:71], v[180:183], v[220:223], v[68:71]
	v_mfma_f32_16x16x32_bf16 v[64:67], v[188:191], v[220:223], v[64:67]
	v_mfma_f32_16x16x32_bf16 v[112:115], v[184:187], v[200:203], v[112:115]
	v_mfma_f32_16x16x32_bf16 v[104:107], v[192:195], v[200:203], v[104:107]
	v_mfma_f32_16x16x32_bf16 v[96:99], v[184:187], v[208:211], v[96:99]
	v_mfma_f32_16x16x32_bf16 v[88:91], v[192:195], v[208:211], v[88:91]
	v_mfma_f32_16x16x32_bf16 v[80:83], v[184:187], v[216:219], v[80:83]
	v_mfma_f32_16x16x32_bf16 v[72:75], v[192:195], v[216:219], v[72:75]
	v_mfma_f32_16x16x32_bf16 v[68:71], v[184:187], v[224:227], v[68:71]
	v_mfma_f32_16x16x32_bf16 v[64:67], v[192:195], v[224:227], v[64:67]
	s_barrier
	s_setprio 0
	s_add_i32 s36, s76, s3
	s_mov_b32 m0, s36
	s_nop 0
	global_load_lds_dwordx4 v132, s[34:35]
	s_add_i32 m0, s36, 0x2000
	s_add_u32 s36, s34, 0x80000
	s_addc_u32 s37, s35, 0
	s_add_i32 s58, s77, s3
	global_load_lds_dwordx4 v128, s[34:35]
	s_mov_b32 m0, s58
	s_nop 0
	global_load_lds_dwordx4 v132, s[36:37]
	s_add_i32 m0, s58, 0x2000
	s_nop 0
	global_load_lds_dwordx4 v128, s[36:37]
	s_mov_b32 m0, s29
	s_nop 0
	global_load_lds_dwordx4 v134, s[48:49]
	s_mov_b32 m0, s53
	s_nop 0
	global_load_lds_dwordx4 v130, s[48:49]
	ds_read_b128 v[196:199], v162 offset:16384
	ds_read_b128 v[200:203], v162 offset:17408
	ds_read_b128 v[204:207], v162 offset:18432
	ds_read_b128 v[208:211], v162 offset:19456
	ds_read_b128 v[212:215], v162 offset:20480
	ds_read_b128 v[216:219], v162 offset:21504
	ds_read_b128 v[220:223], v162 offset:22528
	ds_read_b128 v[224:227], v162 offset:23552
	s_waitcnt vmcnt(8)
	s_waitcnt lgkmcnt(0)
	s_setprio 1
	s_barrier
	v_mfma_f32_16x16x32_bf16 v[60:63], v[144:147], v[196:199], v[60:63]
	v_mfma_f32_16x16x32_bf16 v[56:59], v[172:175], v[196:199], v[56:59]
	v_mfma_f32_16x16x32_bf16 v[52:55], v[144:147], v[204:207], v[52:55]
	v_mfma_f32_16x16x32_bf16 v[44:47], v[172:175], v[204:207], v[44:47]
	v_mfma_f32_16x16x32_bf16 v[36:39], v[144:147], v[212:215], v[36:39]
	v_mfma_f32_16x16x32_bf16 v[28:31], v[172:175], v[212:215], v[28:31]
	v_mfma_f32_16x16x32_bf16 v[20:23], v[144:147], v[220:223], v[20:23]
	v_mfma_f32_16x16x32_bf16 v[12:15], v[172:175], v[220:223], v[12:15]
	v_mfma_f32_16x16x32_bf16 v[60:63], v[164:167], v[200:203], v[60:63]
	v_mfma_f32_16x16x32_bf16 v[56:59], v[176:179], v[200:203], v[56:59]
	v_mfma_f32_16x16x32_bf16 v[52:55], v[164:167], v[208:211], v[52:55]
	v_mfma_f32_16x16x32_bf16 v[44:47], v[176:179], v[208:211], v[44:47]
	v_mfma_f32_16x16x32_bf16 v[36:39], v[164:167], v[216:219], v[36:39]
	v_mfma_f32_16x16x32_bf16 v[28:31], v[176:179], v[216:219], v[28:31]
	v_mfma_f32_16x16x32_bf16 v[20:23], v[164:167], v[224:227], v[20:23]
	v_mfma_f32_16x16x32_bf16 v[12:15], v[176:179], v[224:227], v[12:15]
	s_setprio 0
	s_setprio 1
	v_mfma_f32_16x16x32_bf16 v[48:51], v[180:183], v[196:199], v[48:51]
	v_mfma_f32_16x16x32_bf16 v[40:43], v[188:191], v[196:199], v[40:43]
	v_mfma_f32_16x16x32_bf16 v[32:35], v[180:183], v[204:207], v[32:35]
	v_mfma_f32_16x16x32_bf16 v[24:27], v[188:191], v[204:207], v[24:27]
	v_mfma_f32_16x16x32_bf16 v[16:19], v[180:183], v[212:215], v[16:19]
	v_mfma_f32_16x16x32_bf16 v[8:11], v[188:191], v[212:215], v[8:11]
	v_mfma_f32_16x16x32_bf16 v[4:7], v[180:183], v[220:223], v[4:7]
	v_mfma_f32_16x16x32_bf16 v[0:3], v[188:191], v[220:223], v[0:3]
	v_mfma_f32_16x16x32_bf16 v[48:51], v[184:187], v[200:203], v[48:51]
	v_mfma_f32_16x16x32_bf16 v[40:43], v[192:195], v[200:203], v[40:43]
	v_mfma_f32_16x16x32_bf16 v[32:35], v[184:187], v[208:211], v[32:35]
	v_mfma_f32_16x16x32_bf16 v[24:27], v[192:195], v[208:211], v[24:27]
	v_mfma_f32_16x16x32_bf16 v[16:19], v[184:187], v[216:219], v[16:19]
	v_mfma_f32_16x16x32_bf16 v[8:11], v[192:195], v[216:219], v[8:11]
	v_mfma_f32_16x16x32_bf16 v[4:7], v[184:187], v[224:227], v[4:7]
	v_mfma_f32_16x16x32_bf16 v[0:3], v[192:195], v[224:227], v[0:3]
	s_barrier
; #define PG8_STAGE(bufoff, gbase, voff) do { _Pragma("unroll") for (int _i = 0; _i < 2; ++_i) \
;         __builtin_amdgcn_global_load_lds((const unsigned*)((const char*)(gbase) + (voff)[_i]), (PG8_LAS unsigned*)(lds + (bufoff) + ldsw + _i * 8192), 16, 0, 0); } while (0)
; #define PG8_LDA(dst, b, h) do { _Pragma("unroll") for (int m = 0; m < 4; ++m) _Pragma("unroll") for (int k = 0; k < 2; ++k) dst[m][k] = *(const PG8_LAS bf16x8*)(lds + PG8_SA(b, h) + aoff + m * 2048 + k * 1024); } while (0)
; #define PG8_LDB(dst, b, h) do { _Pragma("unroll") for (int n = 0; n < 2; ++n) _Pragma("unroll") for (int k = 0; k < 2; ++k) dst[n][k] = *(const PG8_LAS bf16x8*)(lds + PG8_SB(b, h) + boff + n * 2048 + k * 1024); } while (0)
; #define PG8_MMA(ai, bj, At, Bt) do { __builtin_amdgcn_s_setprio(1); _Pragma("unroll") for (int m = 0; m < 4; ++m) _Pragma("unroll") for (int n = 0; n < 2; ++n) _Pragma("unroll") for (int k = 0; k < 2; ++k) \
;         acc[ai][bj][m][n] = __builtin_amdgcn_mfma_f32_16x16x32_bf16(Bt[n][k], At[m][k], acc[ai][bj][m][n], 0, 0, 0); __builtin_amdgcn_s_setprio(0); } while (0)
; #define PG8_WAIT_V(n) asm volatile("s_waitcnt vmcnt(" #n ")" ::: "memory")
; #define PG8_WAIT_L(n) asm volatile("s_waitcnt lgkmcnt(" #n ")" ::: "memory")
; #define PG8_BAR __builtin_amdgcn_s_barrier()
; #define PG8_SCHED __builtin_amdgcn_sched_barrier(0)
; template <class Epi, class Sched, bool ALIGN_EPI = false, bool SP2 = false>
; __device__ __forceinline__ void gemm_phase(PG8_LAS unsigned char* lds, const Gemm g, const Sched& S, const Epi& E) {
;     ...
;             PG8_LDB(B0, 1, 0); PG8_LDB(B1, 1, 1); PG8_SCHED; PG8_LDA(At, 1, 0); PG8_STAGE(PG8_SA(0, 1), a2 + hstep, voffA);
;             PG8_WAIT_V(8); PG8_WAIT_L(0); PG8_BAR; PG8_MMA(0, 0, At, B0); PG8_MMA(0, 1, At, B1); PG8_BAR; PG8_SCHED;
;             PG8_LDA(At, 1, 1); PG8_STAGE(PG8_SB(1, 0), b3, voffB); PG8_STAGE(PG8_SB(1, 1), b3 + hstep, voffB); PG8_STAGE(PG8_SA(1, 0), a3, voffA);
;             PG8_WAIT_V(8); PG8_WAIT_L(0); PG8_BAR; PG8_MMA(1, 0, At, B0); PG8_MMA(1, 1, At, B1); PG8_BAR; PG8_SCHED;
;     ...
;         }
;         if constexpr (ALIGN_EPI) { if (wr == 0) PG8_BAR; }
	s_setprio 0
	s_add_i32 s58, 0, 0x18000
	s_add_i32 s59, 0, 0x1c000
	s_add_u32 s36, s48, 0x80000
	s_addc_u32 s37, s49, 0
	s_mov_b32 m0, s54
	s_nop 0
	global_load_lds_dwordx4 v134, s[36:37]
	s_mov_b32 m0, s55
	s_nop 0
	global_load_lds_dwordx4 v130, s[36:37]
	v_add_u32_e32 v163, s58, v158
	ds_read_b128 v[144:147], v163
	ds_read_b128 v[164:167], v163 offset:1024
	ds_read_b128 v[172:175], v163 offset:2048
	ds_read_b128 v[176:179], v163 offset:3072
	v_add_u32_e32 v163, s59, v158
	ds_read_b128 v[180:183], v163
	ds_read_b128 v[184:187], v163 offset:1024
	ds_read_b128 v[188:191], v163 offset:2048
	ds_read_b128 v[192:195], v163 offset:3072
	ds_read_b128 v[196:199], v162 offset:32768
	ds_read_b128 v[200:203], v162 offset:33792
	ds_read_b128 v[204:207], v162 offset:34816
	ds_read_b128 v[208:211], v162 offset:35840
	ds_read_b128 v[212:215], v162 offset:36864
	ds_read_b128 v[216:219], v162 offset:37888
	ds_read_b128 v[220:223], v162 offset:38912
	ds_read_b128 v[224:227], v162 offset:39936
	s_waitcnt vmcnt(8)
	s_waitcnt lgkmcnt(0)
	s_setprio 1
	s_barrier
	v_mfma_f32_16x16x32_bf16 v[124:127], v[144:147], v[196:199], v[124:127]
	v_mfma_f32_16x16x32_bf16 v[120:123], v[172:175], v[196:199], v[120:123]
	v_mfma_f32_16x16x32_bf16 v[116:119], v[144:147], v[204:207], v[116:119]
	v_mfma_f32_16x16x32_bf16 v[108:111], v[172:175], v[204:207], v[108:111]
	v_mfma_f32_16x16x32_bf16 v[100:103], v[144:147], v[212:215], v[100:103]
	v_mfma_f32_16x16x32_bf16 v[92:95], v[172:175], v[212:215], v[92:95]
	v_mfma_f32_16x16x32_bf16 v[84:87], v[144:147], v[220:223], v[84:87]
	v_mfma_f32_16x16x32_bf16 v[76:79], v[172:175], v[220:223], v[76:79]
	v_mfma_f32_16x16x32_bf16 v[124:127], v[164:167], v[200:203], v[124:127]
	v_mfma_f32_16x16x32_bf16 v[120:123], v[176:179], v[200:203], v[120:123]
	v_mfma_f32_16x16x32_bf16 v[116:119], v[164:167], v[208:211], v[116:119]
	v_mfma_f32_16x16x32_bf16 v[108:111], v[176:179], v[208:211], v[108:111]
	v_mfma_f32_16x16x32_bf16 v[100:103], v[164:167], v[216:219], v[100:103]
	v_mfma_f32_16x16x32_bf16 v[92:95], v[176:179], v[216:219], v[92:95]
	v_mfma_f32_16x16x32_bf16 v[84:87], v[164:167], v[224:227], v[84:87]
	v_mfma_f32_16x16x32_bf16 v[76:79], v[176:179], v[224:227], v[76:79]
	s_setprio 0
	s_setprio 1
	v_mfma_f32_16x16x32_bf16 v[112:115], v[180:183], v[196:199], v[112:115]
	v_mfma_f32_16x16x32_bf16 v[104:107], v[188:191], v[196:199], v[104:107]
	v_mfma_f32_16x16x32_bf16 v[96:99], v[180:183], v[204:207], v[96:99]
	v_mfma_f32_16x16x32_bf16 v[88:91], v[188:191], v[204:207], v[88:91]
	v_mfma_f32_16x16x32_bf16 v[80:83], v[180:183], v[212:215], v[80:83]
	v_mfma_f32_16x16x32_bf16 v[72:75], v[188:191], v[212:215], v[72:75]
	v_mfma_f32_16x16x32_bf16 v[68:71], v[180:183], v[220:223], v[68:71]
	v_mfma_f32_16x16x32_bf16 v[64:67], v[188:191], v[220:223], v[64:67]
	v_mfma_f32_16x16x32_bf16 v[112:115], v[184:187], v[200:203], v[112:115]
	v_mfma_f32_16x16x32_bf16 v[104:107], v[192:195], v[200:203], v[104:107]
	v_mfma_f32_16x16x32_bf16 v[96:99], v[184:187], v[208:211], v[96:99]
	v_mfma_f32_16x16x32_bf16 v[88:91], v[192:195], v[208:211], v[88:91]
	v_mfma_f32_16x16x32_bf16 v[80:83], v[184:187], v[216:219], v[80:83]
	v_mfma_f32_16x16x32_bf16 v[72:75], v[192:195], v[216:219], v[72:75]
	v_mfma_f32_16x16x32_bf16 v[68:71], v[184:187], v[224:227], v[68:71]
	v_mfma_f32_16x16x32_bf16 v[64:67], v[192:195], v[224:227], v[64:67]
	s_barrier
	s_setprio 0
	s_add_i32 s36, s58, s3
	s_add_i32 m0, s36, 0xffffff80
	s_nop 0
	global_load_lds_dwordx4 v132, s[34:35] offset:128
	s_add_i32 m0, s36, 0x1f80
	s_nop 0
	global_load_lds_dwordx4 v128, s[34:35] offset:128
	s_add_u32 s34, s34, 0x80080
	s_addc_u32 s35, s35, 0
	s_add_i32 s36, s59, s3
	s_mov_b32 m0, s36
	s_nop 0
	global_load_lds_dwordx4 v132, s[34:35]
	s_add_i32 m0, s36, 0x2000
	s_nop 0
	global_load_lds_dwordx4 v128, s[34:35]
	s_add_i32 m0, s68, 0xffffff80
	s_nop 0
	global_load_lds_dwordx4 v134, s[48:49] offset:128
	s_add_i32 m0, s69, 0xffffff80
	s_nop 0
	global_load_lds_dwordx4 v130, s[48:49] offset:128
	ds_read_b128 v[196:199], v162 offset:49152
	ds_read_b128 v[200:203], v162 offset:50176
	ds_read_b128 v[204:207], v162 offset:51200
	ds_read_b128 v[208:211], v162 offset:52224
	ds_read_b128 v[212:215], v162 offset:53248
	ds_read_b128 v[216:219], v162 offset:54272
	ds_read_b128 v[220:223], v162 offset:55296
	ds_read_b128 v[224:227], v162 offset:56320
	s_waitcnt vmcnt(8)
	s_waitcnt lgkmcnt(0)
	s_setprio 1
	s_barrier
	v_mfma_f32_16x16x32_bf16 v[60:63], v[144:147], v[196:199], v[60:63]
	v_mfma_f32_16x16x32_bf16 v[56:59], v[172:175], v[196:199], v[56:59]
	v_mfma_f32_16x16x32_bf16 v[52:55], v[144:147], v[204:207], v[52:55]
	v_mfma_f32_16x16x32_bf16 v[44:47], v[172:175], v[204:207], v[44:47]
	v_mfma_f32_16x16x32_bf16 v[36:39], v[144:147], v[212:215], v[36:39]
	v_mfma_f32_16x16x32_bf16 v[28:31], v[172:175], v[212:215], v[28:31]
	v_mfma_f32_16x16x32_bf16 v[20:23], v[144:147], v[220:223], v[20:23]
	v_mfma_f32_16x16x32_bf16 v[12:15], v[172:175], v[220:223], v[12:15]
	v_mfma_f32_16x16x32_bf16 v[60:63], v[164:167], v[200:203], v[60:63]
	v_mfma_f32_16x16x32_bf16 v[56:59], v[176:179], v[200:203], v[56:59]
	v_mfma_f32_16x16x32_bf16 v[52:55], v[164:167], v[208:211], v[52:55]
	v_mfma_f32_16x16x32_bf16 v[44:47], v[176:179], v[208:211], v[44:47]
	v_mfma_f32_16x16x32_bf16 v[36:39], v[164:167], v[216:219], v[36:39]
	v_mfma_f32_16x16x32_bf16 v[28:31], v[176:179], v[216:219], v[28:31]
	v_mfma_f32_16x16x32_bf16 v[20:23], v[164:167], v[224:227], v[20:23]
	v_mfma_f32_16x16x32_bf16 v[12:15], v[176:179], v[224:227], v[12:15]
	s_setprio 0
	s_setprio 1
	v_mfma_f32_16x16x32_bf16 v[48:51], v[180:183], v[196:199], v[48:51]
	v_mfma_f32_16x16x32_bf16 v[40:43], v[188:191], v[196:199], v[40:43]
	v_mfma_f32_16x16x32_bf16 v[32:35], v[180:183], v[204:207], v[32:35]
	v_mfma_f32_16x16x32_bf16 v[24:27], v[188:191], v[204:207], v[24:27]
	v_mfma_f32_16x16x32_bf16 v[16:19], v[180:183], v[212:215], v[16:19]
	v_mfma_f32_16x16x32_bf16 v[8:11], v[188:191], v[212:215], v[8:11]
	v_mfma_f32_16x16x32_bf16 v[4:7], v[180:183], v[220:223], v[4:7]
	v_mfma_f32_16x16x32_bf16 v[0:3], v[188:191], v[220:223], v[0:3]
	v_mfma_f32_16x16x32_bf16 v[48:51], v[184:187], v[200:203], v[48:51]
	v_mfma_f32_16x16x32_bf16 v[40:43], v[192:195], v[200:203], v[40:43]
	v_mfma_f32_16x16x32_bf16 v[32:35], v[184:187], v[208:211], v[32:35]
	v_mfma_f32_16x16x32_bf16 v[24:27], v[192:195], v[208:211], v[24:27]
	v_mfma_f32_16x16x32_bf16 v[16:19], v[184:187], v[216:219], v[16:19]
	v_mfma_f32_16x16x32_bf16 v[8:11], v[192:195], v[216:219], v[8:11]
	v_mfma_f32_16x16x32_bf16 v[4:7], v[184:187], v[224:227], v[4:7]
	v_mfma_f32_16x16x32_bf16 v[0:3], v[192:195], v[224:227], v[0:3]
	s_barrier
	s_setprio 0
	s_add_i32 s84, s84, 2
	s_add_u32 s30, s30, 0x100
	s_addc_u32 s31, s31, 0
	s_add_u32 s82, s82, 0x100
	s_addc_u32 s83, s83, 0
	s_cmp_gt_u32 s84, 29
	s_cbranch_scc0 .LBB0_139
	s_and_b64 vcc, exec, s[14:15]
	s_cbranch_vccz .LBB0_142
	s_barrier

; #define PG8_STAGE(bufoff, gbase, voff) do { _Pragma("unroll") for (int _i = 0; _i < 2; ++_i) \
;         __builtin_amdgcn_global_load_lds((const unsigned*)((const char*)(gbase) + (voff)[_i]), (PG8_LAS unsigned*)(lds + (bufoff) + ldsw + _i * 8192), 16, 0, 0); } while (0)
; #define PG8_LDA(dst, b, h) do { _Pragma("unroll") for (int m = 0; m < 4; ++m) _Pragma("unroll") for (int k = 0; k < 2; ++k) dst[m][k] = *(const PG8_LAS bf16x8*)(lds + PG8_SA(b, h) + aoff + m * 2048 + k * 1024); } while (0)
; #define PG8_LDB(dst, b, h) do { _Pragma("unroll") for (int n = 0; n < 2; ++n) _Pragma("unroll") for (int k = 0; k < 2; ++k) dst[n][k] = *(const PG8_LAS bf16x8*)(lds + PG8_SB(b, h) + boff + n * 2048 + k * 1024); } while (0)
; #define PG8_MMA(ai, bj, At, Bt) do { __builtin_amdgcn_s_setprio(1); _Pragma("unroll") for (int m = 0; m < 4; ++m) _Pragma("unroll") for (int n = 0; n < 2; ++n) _Pragma("unroll") for (int k = 0; k < 2; ++k) \
;         acc[ai][bj][m][n] = __builtin_amdgcn_mfma_f32_16x16x32_bf16(Bt[n][k], At[m][k], acc[ai][bj][m][n], 0, 0, 0); __builtin_amdgcn_s_setprio(0); } while (0)
; #define PG8_WAIT_V(n) asm volatile("s_waitcnt vmcnt(" #n ")" ::: "memory")
; #define PG8_WAIT_L(n) asm volatile("s_waitcnt lgkmcnt(" #n ")" ::: "memory")
; #define PG8_BAR __builtin_amdgcn_s_barrier()
; #define PG8_SCHED __builtin_amdgcn_sched_barrier(0)
; template <class Epi, class Sched, bool ALIGN_EPI = false, bool SP2 = false>
; __device__ __forceinline__ void gemm_phase(PG8_LAS unsigned char* lds, const Gemm g, const Sched& S, const Epi& E) {
;     ...
;             PG8_LDB(B0, 0, 0); PG8_LDB(B1, 0, 1); PG8_SCHED; PG8_LDA(At, 0, 0); PG8_STAGE(PG8_SA(1, 1), a1 + hstep, voffA);
;             PG8_WAIT_V(8); PG8_WAIT_L(0); PG8_BAR; PG8_MMA(0, 0, At, B0); PG8_MMA(0, 1, At, B1); PG8_BAR; PG8_SCHED;
;             PG8_LDA(At, 0, 1); PG8_STAGE(PG8_SB(0, 0), b2, voffB); PG8_STAGE(PG8_SB(0, 1), b2 + hstep, voffB); PG8_STAGE(PG8_SA(0, 0), a2, voffA);
;             PG8_WAIT_V(8); PG8_WAIT_L(0); PG8_BAR; PG8_MMA(1, 0, At, B0); PG8_MMA(1, 1, At, B1); PG8_BAR; PG8_SCHED;
.LBB0_393:
	s_add_u32 s34, s30, 0xfff80080
	s_addc_u32 s35, s31, -1
	s_cmp_eq_u32 s81, 28
	s_cselect_b32 s49, s23, s35
	s_cselect_b32 s48, s77, s34
	s_cselect_b32 s35, s21, s80
	s_cselect_b32 s34, s78, s79
	s_add_i32 m0, s29, 0xc000
	s_nop 0
	global_load_lds_dwordx4 v138, s[30:31]
	s_add_i32 m0, s29, 0xe000
	s_nop 0
	global_load_lds_dwordx4 v140, s[30:31]
	ds_read_b128 v[146:149], v156
	ds_read_b128 v[150:153], v156 offset:1024
	ds_read_b128 v[160:163], v156 offset:2048
	ds_read_b128 v[164:167], v156 offset:3072
	ds_read_b128 v[172:175], v157
	ds_read_b128 v[176:179], v157 offset:1024
	ds_read_b128 v[180:183], v157 offset:2048
	ds_read_b128 v[184:187], v157 offset:3072
	ds_read_b128 v[188:191], v158
	ds_read_b128 v[192:195], v158 offset:1024
	ds_read_b128 v[196:199], v158 offset:2048
	ds_read_b128 v[200:203], v158 offset:3072
	ds_read_b128 v[204:207], v158 offset:4096
	ds_read_b128 v[208:211], v158 offset:5120
	ds_read_b128 v[212:215], v158 offset:6144
	ds_read_b128 v[216:219], v158 offset:7168
	s_waitcnt vmcnt(8)
	s_waitcnt lgkmcnt(0)
	s_setprio 1
	s_barrier
	v_mfma_f32_16x16x32_bf16 v[124:127], v[146:149], v[188:191], v[124:127]
	v_mfma_f32_16x16x32_bf16 v[120:123], v[160:163], v[188:191], v[120:123]
	v_mfma_f32_16x16x32_bf16 v[116:119], v[146:149], v[196:199], v[116:119]
	v_mfma_f32_16x16x32_bf16 v[112:115], v[160:163], v[196:199], v[112:115]
	v_mfma_f32_16x16x32_bf16 v[108:111], v[146:149], v[204:207], v[108:111]
	v_mfma_f32_16x16x32_bf16 v[104:107], v[160:163], v[204:207], v[104:107]
	v_mfma_f32_16x16x32_bf16 v[100:103], v[146:149], v[212:215], v[100:103]
	v_mfma_f32_16x16x32_bf16 v[96:99], v[160:163], v[212:215], v[96:99]
	v_mfma_f32_16x16x32_bf16 v[124:127], v[150:153], v[192:195], v[124:127]
	v_mfma_f32_16x16x32_bf16 v[120:123], v[164:167], v[192:195], v[120:123]
	v_mfma_f32_16x16x32_bf16 v[116:119], v[150:153], v[200:203], v[116:119]
	v_mfma_f32_16x16x32_bf16 v[112:115], v[164:167], v[200:203], v[112:115]
	v_mfma_f32_16x16x32_bf16 v[108:111], v[150:153], v[208:211], v[108:111]
	v_mfma_f32_16x16x32_bf16 v[104:107], v[164:167], v[208:211], v[104:107]
	v_mfma_f32_16x16x32_bf16 v[100:103], v[150:153], v[216:219], v[100:103]
	v_mfma_f32_16x16x32_bf16 v[96:99], v[164:167], v[216:219], v[96:99]
	s_setprio 0
	s_setprio 1
	v_mfma_f32_16x16x32_bf16 v[60:63], v[172:175], v[188:191], v[60:63]
	v_mfma_f32_16x16x32_bf16 v[56:59], v[180:183], v[188:191], v[56:59]
	v_mfma_f32_16x16x32_bf16 v[52:55], v[172:175], v[196:199], v[52:55]
	v_mfma_f32_16x16x32_bf16 v[48:51], v[180:183], v[196:199], v[48:51]
	v_mfma_f32_16x16x32_bf16 v[44:47], v[172:175], v[204:207], v[44:47]
	v_mfma_f32_16x16x32_bf16 v[40:43], v[180:183], v[204:207], v[40:43]
	v_mfma_f32_16x16x32_bf16 v[36:39], v[172:175], v[212:215], v[36:39]
	v_mfma_f32_16x16x32_bf16 v[32:35], v[180:183], v[212:215], v[32:35]
	v_mfma_f32_16x16x32_bf16 v[60:63], v[176:179], v[192:195], v[60:63]
	v_mfma_f32_16x16x32_bf16 v[56:59], v[184:187], v[192:195], v[56:59]
	v_mfma_f32_16x16x32_bf16 v[52:55], v[176:179], v[200:203], v[52:55]
	v_mfma_f32_16x16x32_bf16 v[48:51], v[184:187], v[200:203], v[48:51]
	v_mfma_f32_16x16x32_bf16 v[44:47], v[176:179], v[208:211], v[44:47]
	v_mfma_f32_16x16x32_bf16 v[40:43], v[184:187], v[208:211], v[40:43]
	v_mfma_f32_16x16x32_bf16 v[36:39], v[176:179], v[216:219], v[36:39]
	v_mfma_f32_16x16x32_bf16 v[32:35], v[184:187], v[216:219], v[32:35]
	s_barrier
	s_setprio 0
	s_add_i32 s36, s74, s19
	s_mov_b32 m0, s36
	s_nop 0
	global_load_lds_dwordx4 v130, s[34:35]
	s_add_i32 m0, s36, 0x2000
	s_add_u32 s36, s34, 0x80000
	s_addc_u32 s37, s35, 0
	s_add_i32 s58, s75, s19
	global_load_lds_dwordx4 v134, s[34:35]
	s_mov_b32 m0, s58
	s_nop 0
	global_load_lds_dwordx4 v130, s[36:37]
	s_add_i32 m0, s58, 0x2000
	s_nop 0
	global_load_lds_dwordx4 v134, s[36:37]
	s_mov_b32 m0, s29
	s_nop 0
	global_load_lds_dwordx4 v128, s[48:49]
	s_mov_b32 m0, s39
	s_nop 0
	global_load_lds_dwordx4 v132, s[48:49]
	ds_read_b128 v[188:191], v158 offset:16384
	ds_read_b128 v[192:195], v158 offset:17408
	ds_read_b128 v[196:199], v158 offset:18432
	ds_read_b128 v[200:203], v158 offset:19456
	ds_read_b128 v[204:207], v158 offset:20480
	ds_read_b128 v[208:211], v158 offset:21504
	ds_read_b128 v[212:215], v158 offset:22528
	ds_read_b128 v[216:219], v158 offset:23552
	s_waitcnt vmcnt(8)
	s_waitcnt lgkmcnt(0)
	s_setprio 1
	s_barrier
	v_mfma_f32_16x16x32_bf16 v[92:95], v[146:149], v[188:191], v[92:95]
	v_mfma_f32_16x16x32_bf16 v[88:91], v[160:163], v[188:191], v[88:91]
	v_mfma_f32_16x16x32_bf16 v[84:87], v[146:149], v[196:199], v[84:87]
	v_mfma_f32_16x16x32_bf16 v[80:83], v[160:163], v[196:199], v[80:83]
	v_mfma_f32_16x16x32_bf16 v[76:79], v[146:149], v[204:207], v[76:79]
	v_mfma_f32_16x16x32_bf16 v[72:75], v[160:163], v[204:207], v[72:75]
	v_mfma_f32_16x16x32_bf16 v[68:71], v[146:149], v[212:215], v[68:71]
	v_mfma_f32_16x16x32_bf16 v[64:67], v[160:163], v[212:215], v[64:67]
	v_mfma_f32_16x16x32_bf16 v[92:95], v[150:153], v[192:195], v[92:95]
	v_mfma_f32_16x16x32_bf16 v[88:91], v[164:167], v[192:195], v[88:91]
	v_mfma_f32_16x16x32_bf16 v[84:87], v[150:153], v[200:203], v[84:87]
	v_mfma_f32_16x16x32_bf16 v[80:83], v[164:167], v[200:203], v[80:83]
	v_mfma_f32_16x16x32_bf16 v[76:79], v[150:153], v[208:211], v[76:79]
	v_mfma_f32_16x16x32_bf16 v[72:75], v[164:167], v[208:211], v[72:75]
	v_mfma_f32_16x16x32_bf16 v[68:71], v[150:153], v[216:219], v[68:71]
	v_mfma_f32_16x16x32_bf16 v[64:67], v[164:167], v[216:219], v[64:67]
	s_setprio 0
	s_setprio 1
	v_mfma_f32_16x16x32_bf16 v[28:31], v[172:175], v[188:191], v[28:31]
	v_mfma_f32_16x16x32_bf16 v[24:27], v[180:183], v[188:191], v[24:27]
	v_mfma_f32_16x16x32_bf16 v[20:23], v[172:175], v[196:199], v[20:23]
	v_mfma_f32_16x16x32_bf16 v[16:19], v[180:183], v[196:199], v[16:19]
	v_mfma_f32_16x16x32_bf16 v[12:15], v[172:175], v[204:207], v[12:15]
	v_mfma_f32_16x16x32_bf16 v[8:11], v[180:183], v[204:207], v[8:11]
	v_mfma_f32_16x16x32_bf16 v[4:7], v[172:175], v[212:215], v[4:7]
	v_mfma_f32_16x16x32_bf16 v[0:3], v[180:183], v[212:215], v[0:3]
	v_mfma_f32_16x16x32_bf16 v[28:31], v[176:179], v[192:195], v[28:31]
	v_mfma_f32_16x16x32_bf16 v[24:27], v[184:187], v[192:195], v[24:27]
	v_mfma_f32_16x16x32_bf16 v[20:23], v[176:179], v[200:203], v[20:23]
	v_mfma_f32_16x16x32_bf16 v[16:19], v[184:187], v[200:203], v[16:19]
	v_mfma_f32_16x16x32_bf16 v[12:15], v[176:179], v[208:211], v[12:15]
	v_mfma_f32_16x16x32_bf16 v[8:11], v[184:187], v[208:211], v[8:11]
	v_mfma_f32_16x16x32_bf16 v[4:7], v[176:179], v[216:219], v[4:7]
	v_mfma_f32_16x16x32_bf16 v[0:3], v[184:187], v[216:219], v[0:3]
	s_barrier
; #define PG8_STAGE(bufoff, gbase, voff) do { _Pragma("unroll") for (int _i = 0; _i < 2; ++_i) \
;         __builtin_amdgcn_global_load_lds((const unsigned*)((const char*)(gbase) + (voff)[_i]), (PG8_LAS unsigned*)(lds + (bufoff) + ldsw + _i * 8192), 16, 0, 0); } while (0)
; #define PG8_LDA(dst, b, h) do { _Pragma("unroll") for (int m = 0; m < 4; ++m) _Pragma("unroll") for (int k = 0; k < 2; ++k) dst[m][k] = *(const PG8_LAS bf16x8*)(lds + PG8_SA(b, h) + aoff + m * 2048 + k * 1024); } while (0)
; #define PG8_LDB(dst, b, h) do { _Pragma("unroll") for (int n = 0; n < 2; ++n) _Pragma("unroll") for (int k = 0; k < 2; ++k) dst[n][k] = *(const PG8_LAS bf16x8*)(lds + PG8_SB(b, h) + boff + n * 2048 + k * 1024); } while (0)
; #define PG8_MMA(ai, bj, At, Bt) do { __builtin_amdgcn_s_setprio(1); _Pragma("unroll") for (int m = 0; m < 4; ++m) _Pragma("unroll") for (int n = 0; n < 2; ++n) _Pragma("unroll") for (int k = 0; k < 2; ++k) \
;         acc[ai][bj][m][n] = __builtin_amdgcn_mfma_f32_16x16x32_bf16(Bt[n][k], At[m][k], acc[ai][bj][m][n], 0, 0, 0); __builtin_amdgcn_s_setprio(0); } while (0)
; #define PG8_WAIT_V(n) asm volatile("s_waitcnt vmcnt(" #n ")" ::: "memory")
; #define PG8_WAIT_L(n) asm volatile("s_waitcnt lgkmcnt(" #n ")" ::: "memory")
; #define PG8_BAR __builtin_amdgcn_s_barrier()
; #define PG8_SCHED __builtin_amdgcn_sched_barrier(0)
; template <class Epi, class Sched, bool ALIGN_EPI = false, bool SP2 = false>
; __device__ __forceinline__ void gemm_phase(PG8_LAS unsigned char* lds, const Gemm g, const Sched& S, const Epi& E) {
;     ...
;             PG8_LDB(B0, 1, 0); PG8_LDB(B1, 1, 1); PG8_SCHED; PG8_LDA(At, 1, 0); PG8_STAGE(PG8_SA(0, 1), a2 + hstep, voffA);
;             PG8_WAIT_V(8); PG8_WAIT_L(0); PG8_BAR; PG8_MMA(0, 0, At, B0); PG8_MMA(0, 1, At, B1); PG8_BAR; PG8_SCHED;
;             PG8_LDA(At, 1, 1); PG8_STAGE(PG8_SB(1, 0), b3, voffB); PG8_STAGE(PG8_SB(1, 1), b3 + hstep, voffB); PG8_STAGE(PG8_SA(1, 0), a3, voffA);
;             PG8_WAIT_V(8); PG8_WAIT_L(0); PG8_BAR; PG8_MMA(1, 0, At, B0); PG8_MMA(1, 1, At, B1); PG8_BAR; PG8_SCHED;
;     ...
;         }
;         if constexpr (ALIGN_EPI) { if (wr == 0) PG8_BAR; }
	s_setprio 0
	s_add_i32 s58, 0, 0x18000
	s_add_i32 s59, 0, 0x1c000
	s_add_u32 s36, s48, 0x80000
	s_addc_u32 s37, s49, 0
	s_mov_b32 m0, s50
	s_nop 0
	global_load_lds_dwordx4 v128, s[36:37]
	s_mov_b32 m0, s51
	s_nop 0
	global_load_lds_dwordx4 v132, s[36:37]
	v_add_u32_e32 v136, s58, v154
	ds_read_b128 v[146:149], v136
	ds_read_b128 v[150:153], v136 offset:1024
	ds_read_b128 v[160:163], v136 offset:2048
	ds_read_b128 v[164:167], v136 offset:3072
	v_add_u32_e32 v136, s59, v154
	ds_read_b128 v[172:175], v136
	ds_read_b128 v[176:179], v136 offset:1024
	ds_read_b128 v[180:183], v136 offset:2048
	ds_read_b128 v[184:187], v136 offset:3072
	ds_read_b128 v[188:191], v158 offset:32768
	ds_read_b128 v[192:195], v158 offset:33792
	ds_read_b128 v[196:199], v158 offset:34816
	ds_read_b128 v[200:203], v158 offset:35840
	ds_read_b128 v[204:207], v158 offset:36864
	ds_read_b128 v[208:211], v158 offset:37888
	ds_read_b128 v[212:215], v158 offset:38912
	ds_read_b128 v[216:219], v158 offset:39936
	s_waitcnt vmcnt(8)
	s_waitcnt lgkmcnt(0)
	s_setprio 1
	s_barrier
	v_mfma_f32_16x16x32_bf16 v[124:127], v[146:149], v[188:191], v[124:127]
	v_mfma_f32_16x16x32_bf16 v[120:123], v[160:163], v[188:191], v[120:123]
	v_mfma_f32_16x16x32_bf16 v[116:119], v[146:149], v[196:199], v[116:119]
	v_mfma_f32_16x16x32_bf16 v[112:115], v[160:163], v[196:199], v[112:115]
	v_mfma_f32_16x16x32_bf16 v[108:111], v[146:149], v[204:207], v[108:111]
	v_mfma_f32_16x16x32_bf16 v[104:107], v[160:163], v[204:207], v[104:107]
	v_mfma_f32_16x16x32_bf16 v[100:103], v[146:149], v[212:215], v[100:103]
	v_mfma_f32_16x16x32_bf16 v[96:99], v[160:163], v[212:215], v[96:99]
	v_mfma_f32_16x16x32_bf16 v[124:127], v[150:153], v[192:195], v[124:127]
	v_mfma_f32_16x16x32_bf16 v[120:123], v[164:167], v[192:195], v[120:123]
	v_mfma_f32_16x16x32_bf16 v[116:119], v[150:153], v[200:203], v[116:119]
	v_mfma_f32_16x16x32_bf16 v[112:115], v[164:167], v[200:203], v[112:115]
	v_mfma_f32_16x16x32_bf16 v[108:111], v[150:153], v[208:211], v[108:111]
	v_mfma_f32_16x16x32_bf16 v[104:107], v[164:167], v[208:211], v[104:107]
	v_mfma_f32_16x16x32_bf16 v[100:103], v[150:153], v[216:219], v[100:103]
	v_mfma_f32_16x16x32_bf16 v[96:99], v[164:167], v[216:219], v[96:99]
	s_setprio 0
	s_setprio 1
	v_mfma_f32_16x16x32_bf16 v[60:63], v[172:175], v[188:191], v[60:63]
	v_mfma_f32_16x16x32_bf16 v[56:59], v[180:183], v[188:191], v[56:59]
	v_mfma_f32_16x16x32_bf16 v[52:55], v[172:175], v[196:199], v[52:55]
	v_mfma_f32_16x16x32_bf16 v[48:51], v[180:183], v[196:199], v[48:51]
	v_mfma_f32_16x16x32_bf16 v[44:47], v[172:175], v[204:207], v[44:47]
	v_mfma_f32_16x16x32_bf16 v[40:43], v[180:183], v[204:207], v[40:43]
	v_mfma_f32_16x16x32_bf16 v[36:39], v[172:175], v[212:215], v[36:39]
	v_mfma_f32_16x16x32_bf16 v[32:35], v[180:183], v[212:215], v[32:35]
	v_mfma_f32_16x16x32_bf16 v[60:63], v[176:179], v[192:195], v[60:63]
	v_mfma_f32_16x16x32_bf16 v[56:59], v[184:187], v[192:195], v[56:59]
	v_mfma_f32_16x16x32_bf16 v[52:55], v[176:179], v[200:203], v[52:55]
	v_mfma_f32_16x16x32_bf16 v[48:51], v[184:187], v[200:203], v[48:51]
	v_mfma_f32_16x16x32_bf16 v[44:47], v[176:179], v[208:211], v[44:47]
	v_mfma_f32_16x16x32_bf16 v[40:43], v[184:187], v[208:211], v[40:43]
	v_mfma_f32_16x16x32_bf16 v[36:39], v[176:179], v[216:219], v[36:39]
	v_mfma_f32_16x16x32_bf16 v[32:35], v[184:187], v[216:219], v[32:35]
	s_barrier
	s_setprio 0
	s_add_i32 s36, s58, s19
	s_add_i32 m0, s36, 0xffffff80
	s_nop 0
	global_load_lds_dwordx4 v130, s[34:35] offset:128
	s_add_i32 m0, s36, 0x1f80
	s_nop 0
	global_load_lds_dwordx4 v134, s[34:35] offset:128
	s_add_u32 s34, s34, 0x80080
	s_addc_u32 s35, s35, 0
	s_add_i32 s36, s59, s19
	s_mov_b32 m0, s36
	s_nop 0
	global_load_lds_dwordx4 v130, s[34:35]
	s_add_i32 m0, s36, 0x2000
	s_nop 0
	global_load_lds_dwordx4 v134, s[34:35]
	s_add_i32 m0, s53, 0xffffff80
	s_nop 0
	global_load_lds_dwordx4 v128, s[48:49] offset:128
	s_add_i32 m0, s54, 0xffffff80
	s_nop 0
	global_load_lds_dwordx4 v132, s[48:49] offset:128
	ds_read_b128 v[188:191], v158 offset:49152
	ds_read_b128 v[192:195], v158 offset:50176
	ds_read_b128 v[196:199], v158 offset:51200
	ds_read_b128 v[200:203], v158 offset:52224
	ds_read_b128 v[204:207], v158 offset:53248
	ds_read_b128 v[208:211], v158 offset:54272
	ds_read_b128 v[212:215], v158 offset:55296
	ds_read_b128 v[216:219], v158 offset:56320
	s_waitcnt vmcnt(8)
	s_waitcnt lgkmcnt(0)
	s_setprio 1
	s_barrier
	v_mfma_f32_16x16x32_bf16 v[92:95], v[146:149], v[188:191], v[92:95]
	v_mfma_f32_16x16x32_bf16 v[88:91], v[160:163], v[188:191], v[88:91]
	v_mfma_f32_16x16x32_bf16 v[84:87], v[146:149], v[196:199], v[84:87]
	v_mfma_f32_16x16x32_bf16 v[80:83], v[160:163], v[196:199], v[80:83]
	v_mfma_f32_16x16x32_bf16 v[76:79], v[146:149], v[204:207], v[76:79]
	v_mfma_f32_16x16x32_bf16 v[72:75], v[160:163], v[204:207], v[72:75]
	v_mfma_f32_16x16x32_bf16 v[68:71], v[146:149], v[212:215], v[68:71]
	v_mfma_f32_16x16x32_bf16 v[64:67], v[160:163], v[212:215], v[64:67]
	v_mfma_f32_16x16x32_bf16 v[92:95], v[150:153], v[192:195], v[92:95]
	v_mfma_f32_16x16x32_bf16 v[88:91], v[164:167], v[192:195], v[88:91]
	v_mfma_f32_16x16x32_bf16 v[84:87], v[150:153], v[200:203], v[84:87]
	v_mfma_f32_16x16x32_bf16 v[80:83], v[164:167], v[200:203], v[80:83]
	v_mfma_f32_16x16x32_bf16 v[76:79], v[150:153], v[208:211], v[76:79]
	v_mfma_f32_16x16x32_bf16 v[72:75], v[164:167], v[208:211], v[72:75]
	v_mfma_f32_16x16x32_bf16 v[68:71], v[150:153], v[216:219], v[68:71]
	v_mfma_f32_16x16x32_bf16 v[64:67], v[164:167], v[216:219], v[64:67]
	s_setprio 0
	s_setprio 1
	v_mfma_f32_16x16x32_bf16 v[28:31], v[172:175], v[188:191], v[28:31]
	v_mfma_f32_16x16x32_bf16 v[24:27], v[180:183], v[188:191], v[24:27]
	v_mfma_f32_16x16x32_bf16 v[20:23], v[172:175], v[196:199], v[20:23]
	v_mfma_f32_16x16x32_bf16 v[16:19], v[180:183], v[196:199], v[16:19]
	v_mfma_f32_16x16x32_bf16 v[12:15], v[172:175], v[204:207], v[12:15]
	v_mfma_f32_16x16x32_bf16 v[8:11], v[180:183], v[204:207], v[8:11]
	v_mfma_f32_16x16x32_bf16 v[4:7], v[172:175], v[212:215], v[4:7]
	v_mfma_f32_16x16x32_bf16 v[0:3], v[180:183], v[212:215], v[0:3]
	v_mfma_f32_16x16x32_bf16 v[28:31], v[176:179], v[192:195], v[28:31]
	v_mfma_f32_16x16x32_bf16 v[24:27], v[184:187], v[192:195], v[24:27]
	v_mfma_f32_16x16x32_bf16 v[20:23], v[176:179], v[200:203], v[20:23]
	v_mfma_f32_16x16x32_bf16 v[16:19], v[184:187], v[200:203], v[16:19]
	v_mfma_f32_16x16x32_bf16 v[12:15], v[176:179], v[208:211], v[12:15]
	v_mfma_f32_16x16x32_bf16 v[8:11], v[184:187], v[208:211], v[8:11]
	v_mfma_f32_16x16x32_bf16 v[4:7], v[176:179], v[216:219], v[4:7]
	v_mfma_f32_16x16x32_bf16 v[0:3], v[184:187], v[216:219], v[0:3]
	s_barrier
	s_setprio 0
	s_add_i32 s81, s81, 2
	s_add_u32 s30, s30, 0x100
	s_addc_u32 s31, s31, 0
	s_add_u32 s79, s79, 0x100
	s_addc_u32 s80, s80, 0
	s_cmp_gt_u32 s81, 29
	s_cbranch_scc0 .LBB0_393
	s_and_b64 vcc, exec, s[16:17]
	s_cbranch_vccz .LBB0_396
	s_barrier

; #define PG8_STAGE(bufoff, gbase, voff) do { _Pragma("unroll") for (int _i = 0; _i < 2; ++_i) \
;         __builtin_amdgcn_global_load_lds((const unsigned*)((const char*)(gbase) + (voff)[_i]), (PG8_LAS unsigned*)(lds + (bufoff) + ldsw + _i * 8192), 16, 0, 0); } while (0)
; #define PG8_LDA(dst, b, h) do { _Pragma("unroll") for (int m = 0; m < 4; ++m) _Pragma("unroll") for (int k = 0; k < 2; ++k) dst[m][k] = *(const PG8_LAS bf16x8*)(lds + PG8_SA(b, h) + aoff + m * 2048 + k * 1024); } while (0)
; #define PG8_LDB(dst, b, h) do { _Pragma("unroll") for (int n = 0; n < 2; ++n) _Pragma("unroll") for (int k = 0; k < 2; ++k) dst[n][k] = *(const PG8_LAS bf16x8*)(lds + PG8_SB(b, h) + boff + n * 2048 + k * 1024); } while (0)
; #define PG8_MMA(ai, bj, At, Bt) do { __builtin_amdgcn_s_setprio(1); _Pragma("unroll") for (int m = 0; m < 4; ++m) _Pragma("unroll") for (int n = 0; n < 2; ++n) _Pragma("unroll") for (int k = 0; k < 2; ++k) \
;         acc[ai][bj][m][n] = __builtin_amdgcn_mfma_f32_16x16x32_bf16(Bt[n][k], At[m][k], acc[ai][bj][m][n], 0, 0, 0); __builtin_amdgcn_s_setprio(0); } while (0)
; #define PG8_WAIT_V(n) asm volatile("s_waitcnt vmcnt(" #n ")" ::: "memory")
; #define PG8_WAIT_L(n) asm volatile("s_waitcnt lgkmcnt(" #n ")" ::: "memory")
; #define PG8_BAR __builtin_amdgcn_s_barrier()
; #define PG8_SCHED __builtin_amdgcn_sched_barrier(0)
; template <class Epi, class Sched, bool ALIGN_EPI = false, bool SP2 = false>
; __device__ __forceinline__ void gemm_phase(PG8_LAS unsigned char* lds, const Gemm g, const Sched& S, const Epi& E) {
;     ...
;             PG8_LDB(B0, 0, 0); PG8_LDB(B1, 0, 1); PG8_SCHED; PG8_LDA(At, 0, 0); PG8_STAGE(PG8_SA(1, 1), a1 + hstep, voffA);
;             PG8_WAIT_V(8); PG8_WAIT_L(0); PG8_BAR; PG8_MMA(0, 0, At, B0); PG8_MMA(0, 1, At, B1); PG8_BAR; PG8_SCHED;
;             PG8_LDA(At, 0, 1); PG8_STAGE(PG8_SB(0, 0), b2, voffB); PG8_STAGE(PG8_SB(0, 1), b2 + hstep, voffB); PG8_STAGE(PG8_SA(0, 0), a2, voffA);
;             PG8_WAIT_V(8); PG8_WAIT_L(0); PG8_BAR; PG8_MMA(1, 0, At, B0); PG8_MMA(1, 1, At, B1); PG8_BAR; PG8_SCHED;
.LBB0_523:
	s_add_u32 s30, s28, 0xfff80080
	s_addc_u32 s31, s29, -1
	s_cmp_eq_u32 s80, 28
	s_cselect_b32 s35, s21, s31
	s_cselect_b32 s34, s76, s30
	s_cselect_b32 s31, s19, s79
	s_cselect_b32 s30, s77, s78
	s_add_i32 m0, s27, 0xc000
	s_nop 0
	global_load_lds_dwordx4 v140, s[28:29]
	s_add_i32 m0, s27, 0xe000
	s_nop 0
	global_load_lds_dwordx4 v142, s[28:29]
	ds_read_b128 v[154:157], v151
	ds_read_b128 v[158:161], v151 offset:1024
	ds_read_b128 v[162:165], v151 offset:2048
	ds_read_b128 v[166:169], v151 offset:3072
	ds_read_b128 v[174:177], v152
	ds_read_b128 v[178:181], v152 offset:1024
	ds_read_b128 v[182:185], v152 offset:2048
	ds_read_b128 v[186:189], v152 offset:3072
	ds_read_b128 v[190:193], v153
	ds_read_b128 v[194:197], v153 offset:1024
	ds_read_b128 v[198:201], v153 offset:2048
	ds_read_b128 v[202:205], v153 offset:3072
	ds_read_b128 v[206:209], v153 offset:4096
	ds_read_b128 v[210:213], v153 offset:5120
	ds_read_b128 v[214:217], v153 offset:6144
	ds_read_b128 v[218:221], v153 offset:7168
	s_waitcnt vmcnt(8)
	s_waitcnt lgkmcnt(0)
	s_setprio 1
	s_barrier
	v_mfma_f32_16x16x32_bf16 v[124:127], v[154:157], v[190:193], v[124:127]
	v_mfma_f32_16x16x32_bf16 v[120:123], v[162:165], v[190:193], v[120:123]
	v_mfma_f32_16x16x32_bf16 v[108:111], v[154:157], v[198:201], v[108:111]
	v_mfma_f32_16x16x32_bf16 v[104:107], v[162:165], v[198:201], v[104:107]
	v_mfma_f32_16x16x32_bf16 v[92:95], v[154:157], v[206:209], v[92:95]
	v_mfma_f32_16x16x32_bf16 v[88:91], v[162:165], v[206:209], v[88:91]
	v_mfma_f32_16x16x32_bf16 v[76:79], v[154:157], v[214:217], v[76:79]
	v_mfma_f32_16x16x32_bf16 v[72:75], v[162:165], v[214:217], v[72:75]
	v_mfma_f32_16x16x32_bf16 v[124:127], v[158:161], v[194:197], v[124:127]
	v_mfma_f32_16x16x32_bf16 v[120:123], v[166:169], v[194:197], v[120:123]
	v_mfma_f32_16x16x32_bf16 v[108:111], v[158:161], v[202:205], v[108:111]
	v_mfma_f32_16x16x32_bf16 v[104:107], v[166:169], v[202:205], v[104:107]
	v_mfma_f32_16x16x32_bf16 v[92:95], v[158:161], v[210:213], v[92:95]
	v_mfma_f32_16x16x32_bf16 v[88:91], v[166:169], v[210:213], v[88:91]
	v_mfma_f32_16x16x32_bf16 v[76:79], v[158:161], v[218:221], v[76:79]
	v_mfma_f32_16x16x32_bf16 v[72:75], v[166:169], v[218:221], v[72:75]
	s_setprio 0
	s_setprio 1
	v_mfma_f32_16x16x32_bf16 v[116:119], v[174:177], v[190:193], v[116:119]
	v_mfma_f32_16x16x32_bf16 v[112:115], v[182:185], v[190:193], v[112:115]
	v_mfma_f32_16x16x32_bf16 v[100:103], v[174:177], v[198:201], v[100:103]
	v_mfma_f32_16x16x32_bf16 v[96:99], v[182:185], v[198:201], v[96:99]
	v_mfma_f32_16x16x32_bf16 v[84:87], v[174:177], v[206:209], v[84:87]
	v_mfma_f32_16x16x32_bf16 v[80:83], v[182:185], v[206:209], v[80:83]
	v_mfma_f32_16x16x32_bf16 v[68:71], v[174:177], v[214:217], v[68:71]
	v_mfma_f32_16x16x32_bf16 v[64:67], v[182:185], v[214:217], v[64:67]
	v_mfma_f32_16x16x32_bf16 v[116:119], v[178:181], v[194:197], v[116:119]
	v_mfma_f32_16x16x32_bf16 v[112:115], v[186:189], v[194:197], v[112:115]
	v_mfma_f32_16x16x32_bf16 v[100:103], v[178:181], v[202:205], v[100:103]
	v_mfma_f32_16x16x32_bf16 v[96:99], v[186:189], v[202:205], v[96:99]
	v_mfma_f32_16x16x32_bf16 v[84:87], v[178:181], v[210:213], v[84:87]
	v_mfma_f32_16x16x32_bf16 v[80:83], v[186:189], v[210:213], v[80:83]
	v_mfma_f32_16x16x32_bf16 v[68:71], v[178:181], v[218:221], v[68:71]
	v_mfma_f32_16x16x32_bf16 v[64:67], v[186:189], v[218:221], v[64:67]
	s_barrier
	s_setprio 0
	s_add_i32 s36, s72, s3
	s_mov_b32 m0, s36
	s_nop 0
	global_load_lds_dwordx4 v132, s[30:31]
	s_add_i32 m0, s36, 0x2000
	s_add_u32 s36, s30, 0x80000
	s_addc_u32 s37, s31, 0
	s_add_i32 s58, s73, s3
	global_load_lds_dwordx4 v128, s[30:31]
	s_mov_b32 m0, s58
	v_lshl_add_u64 v[226:227], s[34:35], 0, v[130:131]
	global_load_lds_dwordx4 v132, s[36:37]
	s_add_i32 m0, s58, 0x2000
	s_nop 0
	global_load_lds_dwordx4 v128, s[36:37]
	v_lshl_add_u64 v[224:225], s[34:35], 0, v[134:135]
	s_mov_b32 m0, s27
	s_nop 0
	global_load_lds_dwordx4 v134, s[34:35]
	s_mov_b32 m0, s49
	s_nop 0
	global_load_lds_dwordx4 v130, s[34:35]
	ds_read_b128 v[190:193], v153 offset:16384
	ds_read_b128 v[194:197], v153 offset:17408
	ds_read_b128 v[198:201], v153 offset:18432
	ds_read_b128 v[202:205], v153 offset:19456
	ds_read_b128 v[206:209], v153 offset:20480
	ds_read_b128 v[210:213], v153 offset:21504
	ds_read_b128 v[214:217], v153 offset:22528
	ds_read_b128 v[218:221], v153 offset:23552
	s_waitcnt vmcnt(8)
	s_waitcnt lgkmcnt(0)
	s_setprio 1
	s_barrier
	v_mfma_f32_16x16x32_bf16 v[60:63], v[154:157], v[190:193], v[60:63]
	v_mfma_f32_16x16x32_bf16 v[56:59], v[162:165], v[190:193], v[56:59]
	v_mfma_f32_16x16x32_bf16 v[44:47], v[154:157], v[198:201], v[44:47]
	v_mfma_f32_16x16x32_bf16 v[40:43], v[162:165], v[198:201], v[40:43]
	v_mfma_f32_16x16x32_bf16 v[28:31], v[154:157], v[206:209], v[28:31]
	v_mfma_f32_16x16x32_bf16 v[24:27], v[162:165], v[206:209], v[24:27]
	v_mfma_f32_16x16x32_bf16 v[12:15], v[154:157], v[214:217], v[12:15]
	v_mfma_f32_16x16x32_bf16 v[8:11], v[162:165], v[214:217], v[8:11]
	v_mfma_f32_16x16x32_bf16 v[60:63], v[158:161], v[194:197], v[60:63]
	v_mfma_f32_16x16x32_bf16 v[56:59], v[166:169], v[194:197], v[56:59]
	v_mfma_f32_16x16x32_bf16 v[44:47], v[158:161], v[202:205], v[44:47]
	v_mfma_f32_16x16x32_bf16 v[40:43], v[166:169], v[202:205], v[40:43]
	v_mfma_f32_16x16x32_bf16 v[28:31], v[158:161], v[210:213], v[28:31]
	v_mfma_f32_16x16x32_bf16 v[24:27], v[166:169], v[210:213], v[24:27]
	v_mfma_f32_16x16x32_bf16 v[12:15], v[158:161], v[218:221], v[12:15]
	v_mfma_f32_16x16x32_bf16 v[8:11], v[166:169], v[218:221], v[8:11]
	s_setprio 0
	s_setprio 1
	v_mfma_f32_16x16x32_bf16 v[52:55], v[174:177], v[190:193], v[52:55]
	v_mfma_f32_16x16x32_bf16 v[48:51], v[182:185], v[190:193], v[48:51]
	v_mfma_f32_16x16x32_bf16 v[36:39], v[174:177], v[198:201], v[36:39]
	v_mfma_f32_16x16x32_bf16 v[32:35], v[182:185], v[198:201], v[32:35]
	v_mfma_f32_16x16x32_bf16 v[20:23], v[174:177], v[206:209], v[20:23]
	v_mfma_f32_16x16x32_bf16 v[16:19], v[182:185], v[206:209], v[16:19]
	v_mfma_f32_16x16x32_bf16 v[4:7], v[174:177], v[214:217], v[4:7]
	v_mfma_f32_16x16x32_bf16 v[0:3], v[182:185], v[214:217], v[0:3]
	v_mfma_f32_16x16x32_bf16 v[52:55], v[178:181], v[194:197], v[52:55]
	v_mfma_f32_16x16x32_bf16 v[48:51], v[186:189], v[194:197], v[48:51]
	v_mfma_f32_16x16x32_bf16 v[36:39], v[178:181], v[202:205], v[36:39]
	v_mfma_f32_16x16x32_bf16 v[32:35], v[186:189], v[202:205], v[32:35]
	v_mfma_f32_16x16x32_bf16 v[20:23], v[178:181], v[210:213], v[20:23]
	v_mfma_f32_16x16x32_bf16 v[16:19], v[186:189], v[210:213], v[16:19]
	v_mfma_f32_16x16x32_bf16 v[4:7], v[178:181], v[218:221], v[4:7]
	v_mfma_f32_16x16x32_bf16 v[0:3], v[186:189], v[218:221], v[0:3]
	s_barrier
; #define PG8_STAGE(bufoff, gbase, voff) do { _Pragma("unroll") for (int _i = 0; _i < 2; ++_i) \
;         __builtin_amdgcn_global_load_lds((const unsigned*)((const char*)(gbase) + (voff)[_i]), (PG8_LAS unsigned*)(lds + (bufoff) + ldsw + _i * 8192), 16, 0, 0); } while (0)
; #define PG8_LDA(dst, b, h) do { _Pragma("unroll") for (int m = 0; m < 4; ++m) _Pragma("unroll") for (int k = 0; k < 2; ++k) dst[m][k] = *(const PG8_LAS bf16x8*)(lds + PG8_SA(b, h) + aoff + m * 2048 + k * 1024); } while (0)
; #define PG8_LDB(dst, b, h) do { _Pragma("unroll") for (int n = 0; n < 2; ++n) _Pragma("unroll") for (int k = 0; k < 2; ++k) dst[n][k] = *(const PG8_LAS bf16x8*)(lds + PG8_SB(b, h) + boff + n * 2048 + k * 1024); } while (0)
; #define PG8_MMA(ai, bj, At, Bt) do { __builtin_amdgcn_s_setprio(1); _Pragma("unroll") for (int m = 0; m < 4; ++m) _Pragma("unroll") for (int n = 0; n < 2; ++n) _Pragma("unroll") for (int k = 0; k < 2; ++k) \
;         acc[ai][bj][m][n] = __builtin_amdgcn_mfma_f32_16x16x32_bf16(Bt[n][k], At[m][k], acc[ai][bj][m][n], 0, 0, 0); __builtin_amdgcn_s_setprio(0); } while (0)
; #define PG8_WAIT_V(n) asm volatile("s_waitcnt vmcnt(" #n ")" ::: "memory")
; #define PG8_WAIT_L(n) asm volatile("s_waitcnt lgkmcnt(" #n ")" ::: "memory")
; #define PG8_BAR __builtin_amdgcn_s_barrier()
; #define PG8_SCHED __builtin_amdgcn_sched_barrier(0)
; template <class Epi, class Sched, bool ALIGN_EPI = false, bool SP2 = false>
; __device__ __forceinline__ void gemm_phase(PG8_LAS unsigned char* lds, const Gemm g, const Sched& S, const Epi& E) {
;     ...
;         for (int t = 0; t < nt; t += 2) {
;     ...
;             PG8_LDB(B0, 1, 0); PG8_LDB(B1, 1, 1); PG8_SCHED; PG8_LDA(At, 1, 0); PG8_STAGE(PG8_SA(0, 1), a2 + hstep, voffA);
;             PG8_WAIT_V(8); PG8_WAIT_L(0); PG8_BAR; PG8_MMA(0, 0, At, B0); PG8_MMA(0, 1, At, B1); PG8_BAR; PG8_SCHED;
;             PG8_LDA(At, 1, 1); PG8_STAGE(PG8_SB(1, 0), b3, voffB); PG8_STAGE(PG8_SB(1, 1), b3 + hstep, voffB); PG8_STAGE(PG8_SA(1, 0), a3, voffA);
;             PG8_WAIT_V(8); PG8_WAIT_L(0); PG8_BAR; PG8_MMA(1, 0, At, B0); PG8_MMA(1, 1, At, B1); PG8_BAR; PG8_SCHED;
	s_setprio 0
	s_add_i32 s36, 0, 0x18000
	s_add_i32 s37, 0, 0x1c000
	s_add_u32 s34, s34, 0x80000
	s_addc_u32 s35, s35, 0
	s_mov_b32 m0, s50
	s_nop 0
	global_load_lds_dwordx4 v134, s[34:35]
	s_mov_b32 m0, s51
	s_nop 0
	global_load_lds_dwordx4 v130, s[34:35]
	v_add_u32_e32 v166, s36, v139
	v_add_u32_e32 v171, s37, v139
	ds_read_b128 v[154:157], v166
	ds_read_b128 v[158:161], v166 offset:1024
	ds_read_b128 v[162:165], v166 offset:2048
	ds_read_b128 v[166:169], v166 offset:3072
	ds_read_b128 v[174:177], v171
	ds_read_b128 v[178:181], v171 offset:1024
	ds_read_b128 v[182:185], v171 offset:2048
	ds_read_b128 v[186:189], v171 offset:3072
	ds_read_b128 v[190:193], v153 offset:32768
	ds_read_b128 v[194:197], v153 offset:33792
	ds_read_b128 v[198:201], v153 offset:34816
	ds_read_b128 v[202:205], v153 offset:35840
	ds_read_b128 v[206:209], v153 offset:36864
	ds_read_b128 v[210:213], v153 offset:37888
	ds_read_b128 v[214:217], v153 offset:38912
	ds_read_b128 v[218:221], v153 offset:39936
	s_waitcnt vmcnt(8)
	s_waitcnt lgkmcnt(0)
	s_setprio 1
	s_barrier
	v_mfma_f32_16x16x32_bf16 v[124:127], v[154:157], v[190:193], v[124:127]
	v_mfma_f32_16x16x32_bf16 v[120:123], v[162:165], v[190:193], v[120:123]
	v_mfma_f32_16x16x32_bf16 v[108:111], v[154:157], v[198:201], v[108:111]
	v_mfma_f32_16x16x32_bf16 v[104:107], v[162:165], v[198:201], v[104:107]
	v_mfma_f32_16x16x32_bf16 v[92:95], v[154:157], v[206:209], v[92:95]
	v_mfma_f32_16x16x32_bf16 v[88:91], v[162:165], v[206:209], v[88:91]
	v_mfma_f32_16x16x32_bf16 v[76:79], v[154:157], v[214:217], v[76:79]
	v_mfma_f32_16x16x32_bf16 v[72:75], v[162:165], v[214:217], v[72:75]
	v_mfma_f32_16x16x32_bf16 v[124:127], v[158:161], v[194:197], v[124:127]
	v_mfma_f32_16x16x32_bf16 v[120:123], v[166:169], v[194:197], v[120:123]
	v_mfma_f32_16x16x32_bf16 v[108:111], v[158:161], v[202:205], v[108:111]
	v_mfma_f32_16x16x32_bf16 v[104:107], v[166:169], v[202:205], v[104:107]
	v_mfma_f32_16x16x32_bf16 v[92:95], v[158:161], v[210:213], v[92:95]
	v_mfma_f32_16x16x32_bf16 v[88:91], v[166:169], v[210:213], v[88:91]
	v_mfma_f32_16x16x32_bf16 v[76:79], v[158:161], v[218:221], v[76:79]
	v_mfma_f32_16x16x32_bf16 v[72:75], v[166:169], v[218:221], v[72:75]
	s_setprio 0
	s_setprio 1
	v_mfma_f32_16x16x32_bf16 v[116:119], v[174:177], v[190:193], v[116:119]
	v_mfma_f32_16x16x32_bf16 v[112:115], v[182:185], v[190:193], v[112:115]
	v_mfma_f32_16x16x32_bf16 v[100:103], v[174:177], v[198:201], v[100:103]
	v_mfma_f32_16x16x32_bf16 v[96:99], v[182:185], v[198:201], v[96:99]
	v_mfma_f32_16x16x32_bf16 v[84:87], v[174:177], v[206:209], v[84:87]
	v_mfma_f32_16x16x32_bf16 v[80:83], v[182:185], v[206:209], v[80:83]
	v_mfma_f32_16x16x32_bf16 v[68:71], v[174:177], v[214:217], v[68:71]
	v_mfma_f32_16x16x32_bf16 v[64:67], v[182:185], v[214:217], v[64:67]
	v_mfma_f32_16x16x32_bf16 v[116:119], v[178:181], v[194:197], v[116:119]
	v_mfma_f32_16x16x32_bf16 v[112:115], v[186:189], v[194:197], v[112:115]
	v_mfma_f32_16x16x32_bf16 v[100:103], v[178:181], v[202:205], v[100:103]
	v_mfma_f32_16x16x32_bf16 v[96:99], v[186:189], v[202:205], v[96:99]
	v_mfma_f32_16x16x32_bf16 v[84:87], v[178:181], v[210:213], v[84:87]
	v_mfma_f32_16x16x32_bf16 v[80:83], v[186:189], v[210:213], v[80:83]
	v_mfma_f32_16x16x32_bf16 v[68:71], v[178:181], v[218:221], v[68:71]
	v_mfma_f32_16x16x32_bf16 v[64:67], v[186:189], v[218:221], v[64:67]
	s_barrier
	s_setprio 0
	s_add_i32 s34, s36, s3
	s_add_i32 m0, s34, 0xffffff80
	s_nop 0
	global_load_lds_dwordx4 v132, s[30:31] offset:128
	s_add_i32 m0, s34, 0x1f80
	s_nop 0
	global_load_lds_dwordx4 v128, s[30:31] offset:128
	s_add_u32 s30, s30, 0x80080
	s_addc_u32 s31, s31, 0
	s_add_i32 s34, s37, s3
	s_mov_b32 m0, s34
	s_nop 0
	global_load_lds_dwordx4 v132, s[30:31]
	s_add_i32 m0, s34, 0x2000
	s_nop 0
	global_load_lds_dwordx4 v128, s[30:31]
	v_lshl_add_u64 v[148:149], v[224:225], 0, s[14:15]
	s_mov_b32 m0, s53
	s_nop 0
	global_load_lds_dwordx4 v[148:149], off
	v_lshl_add_u64 v[148:149], v[226:227], 0, s[14:15]
	s_mov_b32 m0, s54
	s_nop 0
	global_load_lds_dwordx4 v[148:149], off
	ds_read_b128 v[190:193], v153 offset:49152
	ds_read_b128 v[194:197], v153 offset:50176
	ds_read_b128 v[198:201], v153 offset:51200
	ds_read_b128 v[202:205], v153 offset:52224
	ds_read_b128 v[206:209], v153 offset:53248
	ds_read_b128 v[210:213], v153 offset:54272
	ds_read_b128 v[214:217], v153 offset:55296
	ds_read_b128 v[218:221], v153 offset:56320
	s_waitcnt vmcnt(8)
	s_waitcnt lgkmcnt(0)
	s_setprio 1
	s_barrier
	v_mfma_f32_16x16x32_bf16 v[60:63], v[154:157], v[190:193], v[60:63]
	v_mfma_f32_16x16x32_bf16 v[56:59], v[162:165], v[190:193], v[56:59]
	v_mfma_f32_16x16x32_bf16 v[44:47], v[154:157], v[198:201], v[44:47]
	v_mfma_f32_16x16x32_bf16 v[40:43], v[162:165], v[198:201], v[40:43]
	v_mfma_f32_16x16x32_bf16 v[28:31], v[154:157], v[206:209], v[28:31]
	v_mfma_f32_16x16x32_bf16 v[24:27], v[162:165], v[206:209], v[24:27]
	v_mfma_f32_16x16x32_bf16 v[12:15], v[154:157], v[214:217], v[12:15]
	v_mfma_f32_16x16x32_bf16 v[8:11], v[162:165], v[214:217], v[8:11]
	v_mfma_f32_16x16x32_bf16 v[60:63], v[158:161], v[194:197], v[60:63]
	v_mfma_f32_16x16x32_bf16 v[56:59], v[166:169], v[194:197], v[56:59]
	v_mfma_f32_16x16x32_bf16 v[44:47], v[158:161], v[202:205], v[44:47]
	v_mfma_f32_16x16x32_bf16 v[40:43], v[166:169], v[202:205], v[40:43]
	v_mfma_f32_16x16x32_bf16 v[28:31], v[158:161], v[210:213], v[28:31]
	v_mfma_f32_16x16x32_bf16 v[24:27], v[166:169], v[210:213], v[24:27]
	v_mfma_f32_16x16x32_bf16 v[12:15], v[158:161], v[218:221], v[12:15]
	v_mfma_f32_16x16x32_bf16 v[8:11], v[166:169], v[218:221], v[8:11]
	s_setprio 0
	s_setprio 1
	v_mfma_f32_16x16x32_bf16 v[52:55], v[174:177], v[190:193], v[52:55]
	v_mfma_f32_16x16x32_bf16 v[48:51], v[182:185], v[190:193], v[48:51]
	v_mfma_f32_16x16x32_bf16 v[36:39], v[174:177], v[198:201], v[36:39]
	v_mfma_f32_16x16x32_bf16 v[32:35], v[182:185], v[198:201], v[32:35]
	v_mfma_f32_16x16x32_bf16 v[20:23], v[174:177], v[206:209], v[20:23]
	v_mfma_f32_16x16x32_bf16 v[16:19], v[182:185], v[206:209], v[16:19]
	v_mfma_f32_16x16x32_bf16 v[4:7], v[174:177], v[214:217], v[4:7]
	v_mfma_f32_16x16x32_bf16 v[0:3], v[182:185], v[214:217], v[0:3]
	v_mfma_f32_16x16x32_bf16 v[52:55], v[178:181], v[194:197], v[52:55]
	v_mfma_f32_16x16x32_bf16 v[48:51], v[186:189], v[194:197], v[48:51]
	v_mfma_f32_16x16x32_bf16 v[36:39], v[178:181], v[202:205], v[36:39]
	v_mfma_f32_16x16x32_bf16 v[32:35], v[186:189], v[202:205], v[32:35]
	v_mfma_f32_16x16x32_bf16 v[20:23], v[178:181], v[210:213], v[20:23]
	v_mfma_f32_16x16x32_bf16 v[16:19], v[186:189], v[210:213], v[16:19]
	v_mfma_f32_16x16x32_bf16 v[4:7], v[178:181], v[218:221], v[4:7]
	v_mfma_f32_16x16x32_bf16 v[0:3], v[186:189], v[218:221], v[0:3]
	s_barrier
	s_setprio 0
	s_add_i32 s80, s80, 2
	s_add_u32 s28, s28, 0x100
	s_addc_u32 s29, s29, 0
	s_add_u32 s78, s78, 0x100
	s_addc_u32 s79, s79, 0
	s_cmp_gt_u32 s80, 29
	s_cbranch_scc0 .LBB0_523
	s_and_b64 vcc, exec, s[16:17]
	s_cbranch_vccz .LBB0_526
	s_barrier

; #define PG8_STAGE(bufoff, gbase, voff) do { _Pragma("unroll") for (int _i = 0; _i < 2; ++_i) \
;         __builtin_amdgcn_global_load_lds((const unsigned*)((const char*)(gbase) + (voff)[_i]), (PG8_LAS unsigned*)(lds + (bufoff) + ldsw + _i * 8192), 16, 0, 0); } while (0)
; #define PG8_LDA(dst, b, h) do { _Pragma("unroll") for (int m = 0; m < 4; ++m) _Pragma("unroll") for (int k = 0; k < 2; ++k) dst[m][k] = *(const PG8_LAS bf16x8*)(lds + PG8_SA(b, h) + aoff + m * 2048 + k * 1024); } while (0)
; #define PG8_LDB(dst, b, h) do { _Pragma("unroll") for (int n = 0; n < 2; ++n) _Pragma("unroll") for (int k = 0; k < 2; ++k) dst[n][k] = *(const PG8_LAS bf16x8*)(lds + PG8_SB(b, h) + boff + n * 2048 + k * 1024); } while (0)
; #define PG8_MMA(ai, bj, At, Bt) do { __builtin_amdgcn_s_setprio(1); _Pragma("unroll") for (int m = 0; m < 4; ++m) _Pragma("unroll") for (int n = 0; n < 2; ++n) _Pragma("unroll") for (int k = 0; k < 2; ++k) \
;         acc[ai][bj][m][n] = __builtin_amdgcn_mfma_f32_16x16x32_bf16(Bt[n][k], At[m][k], acc[ai][bj][m][n], 0, 0, 0); __builtin_amdgcn_s_setprio(0); } while (0)
; #define PG8_WAIT_V(n) asm volatile("s_waitcnt vmcnt(" #n ")" ::: "memory")
; #define PG8_WAIT_L(n) asm volatile("s_waitcnt lgkmcnt(" #n ")" ::: "memory")
; #define PG8_BAR __builtin_amdgcn_s_barrier()
; #define PG8_SCHED __builtin_amdgcn_sched_barrier(0)
; template <class Epi, class Sched, bool ALIGN_EPI = false, bool SP2 = false>
; __device__ __forceinline__ void gemm_phase(PG8_LAS unsigned char* lds, const Gemm g, const Sched& S, const Epi& E) {
;     ...
;             PG8_LDB(B0, 0, 0); PG8_LDB(B1, 0, 1); PG8_SCHED; PG8_LDA(At, 0, 0); PG8_STAGE(PG8_SA(1, 1), a1 + hstep, voffA);
;             PG8_WAIT_V(8); PG8_WAIT_L(0); PG8_BAR; PG8_MMA(0, 0, At, B0); PG8_MMA(0, 1, At, B1); PG8_BAR; PG8_SCHED;
;             PG8_LDA(At, 0, 1); PG8_STAGE(PG8_SB(0, 0), b2, voffB); PG8_STAGE(PG8_SB(0, 1), b2 + hstep, voffB); PG8_STAGE(PG8_SA(0, 0), a2, voffA);
;             PG8_WAIT_V(8); PG8_WAIT_L(0); PG8_BAR; PG8_MMA(1, 0, At, B0); PG8_MMA(1, 1, At, B1); PG8_BAR; PG8_SCHED;
.LBB0_606:
	s_add_u32 s26, s24, 0xffea0080
	s_addc_u32 s27, s25, -1
	s_cmpk_eq_i32 s73, 0x54
	s_cselect_b32 s29, s7, s27
	s_cselect_b32 s28, s6, s26
	s_cselect_b32 s27, s23, s72
	s_cselect_b32 s26, s22, s67
	s_add_i32 m0, s30, 0xc000
	s_nop 0
	global_load_lds_dwordx4 v142, s[24:25]
	s_add_i32 m0, s30, 0xe000
	s_nop 0
	global_load_lds_dwordx4 v144, s[24:25]
	ds_read_b128 v[150:153], v158
	ds_read_b128 v[154:157], v158 offset:1024
	ds_read_b128 v[162:165], v158 offset:2048
	ds_read_b128 v[166:169], v158 offset:3072
	ds_read_b128 v[174:177], v159
	ds_read_b128 v[178:181], v159 offset:1024
	ds_read_b128 v[182:185], v159 offset:2048
	ds_read_b128 v[186:189], v159 offset:3072
	ds_read_b128 v[190:193], v160
	ds_read_b128 v[194:197], v160 offset:1024
	ds_read_b128 v[198:201], v160 offset:2048
	ds_read_b128 v[202:205], v160 offset:3072
	ds_read_b128 v[206:209], v160 offset:4096
	ds_read_b128 v[210:213], v160 offset:5120
	ds_read_b128 v[214:217], v160 offset:6144
	ds_read_b128 v[218:221], v160 offset:7168
	s_waitcnt vmcnt(8)
	s_waitcnt lgkmcnt(0)
	s_setprio 1
	s_barrier
	v_mfma_f32_16x16x32_bf16 v[124:127], v[150:153], v[190:193], v[124:127]
	v_mfma_f32_16x16x32_bf16 v[120:123], v[162:165], v[190:193], v[120:123]
	v_mfma_f32_16x16x32_bf16 v[116:119], v[150:153], v[198:201], v[116:119]
	v_mfma_f32_16x16x32_bf16 v[112:115], v[162:165], v[198:201], v[112:115]
	v_mfma_f32_16x16x32_bf16 v[108:111], v[150:153], v[206:209], v[108:111]
	v_mfma_f32_16x16x32_bf16 v[104:107], v[162:165], v[206:209], v[104:107]
	v_mfma_f32_16x16x32_bf16 v[100:103], v[150:153], v[214:217], v[100:103]
	v_mfma_f32_16x16x32_bf16 v[96:99], v[162:165], v[214:217], v[96:99]
	v_mfma_f32_16x16x32_bf16 v[124:127], v[154:157], v[194:197], v[124:127]
	v_mfma_f32_16x16x32_bf16 v[120:123], v[166:169], v[194:197], v[120:123]
	v_mfma_f32_16x16x32_bf16 v[116:119], v[154:157], v[202:205], v[116:119]
	v_mfma_f32_16x16x32_bf16 v[112:115], v[166:169], v[202:205], v[112:115]
	v_mfma_f32_16x16x32_bf16 v[108:111], v[154:157], v[210:213], v[108:111]
	v_mfma_f32_16x16x32_bf16 v[104:107], v[166:169], v[210:213], v[104:107]
	v_mfma_f32_16x16x32_bf16 v[100:103], v[154:157], v[218:221], v[100:103]
	v_mfma_f32_16x16x32_bf16 v[96:99], v[166:169], v[218:221], v[96:99]
	s_setprio 0
	s_setprio 1
	v_mfma_f32_16x16x32_bf16 v[60:63], v[174:177], v[190:193], v[60:63]
	v_mfma_f32_16x16x32_bf16 v[56:59], v[182:185], v[190:193], v[56:59]
	v_mfma_f32_16x16x32_bf16 v[52:55], v[174:177], v[198:201], v[52:55]
	v_mfma_f32_16x16x32_bf16 v[48:51], v[182:185], v[198:201], v[48:51]
	v_mfma_f32_16x16x32_bf16 v[44:47], v[174:177], v[206:209], v[44:47]
	v_mfma_f32_16x16x32_bf16 v[40:43], v[182:185], v[206:209], v[40:43]
	v_mfma_f32_16x16x32_bf16 v[36:39], v[174:177], v[214:217], v[36:39]
	v_mfma_f32_16x16x32_bf16 v[32:35], v[182:185], v[214:217], v[32:35]
	v_mfma_f32_16x16x32_bf16 v[60:63], v[178:181], v[194:197], v[60:63]
	v_mfma_f32_16x16x32_bf16 v[56:59], v[186:189], v[194:197], v[56:59]
	v_mfma_f32_16x16x32_bf16 v[52:55], v[178:181], v[202:205], v[52:55]
	v_mfma_f32_16x16x32_bf16 v[48:51], v[186:189], v[202:205], v[48:51]
	v_mfma_f32_16x16x32_bf16 v[44:47], v[178:181], v[210:213], v[44:47]
	v_mfma_f32_16x16x32_bf16 v[40:43], v[186:189], v[210:213], v[40:43]
	v_mfma_f32_16x16x32_bf16 v[36:39], v[178:181], v[218:221], v[36:39]
	v_mfma_f32_16x16x32_bf16 v[32:35], v[186:189], v[218:221], v[32:35]
	s_barrier
	s_setprio 0
	s_add_i32 s36, s52, s21
	s_mov_b32 m0, s36
	s_nop 0
	global_load_lds_dwordx4 v130, s[26:27]
	s_add_i32 m0, s36, 0x2000
	s_add_u32 s36, s26, 0x160000
	s_addc_u32 s37, s27, 0
	s_add_i32 s58, s53, s21
	global_load_lds_dwordx4 v134, s[26:27]
	s_mov_b32 m0, s58
	v_lshl_add_u64 v[228:229], s[28:29], 0, v[132:133]
	global_load_lds_dwordx4 v130, s[36:37]
	s_add_i32 m0, s58, 0x2000
	s_nop 0
	global_load_lds_dwordx4 v134, s[36:37]
	v_lshl_add_u64 v[226:227], s[28:29], 0, v[128:129]
	s_mov_b32 m0, s30
	s_nop 0
	global_load_lds_dwordx4 v128, s[28:29]
	s_mov_b32 m0, s31
	s_nop 0
	global_load_lds_dwordx4 v132, s[28:29]
	ds_read_b128 v[190:193], v160 offset:16384
	ds_read_b128 v[194:197], v160 offset:17408
	ds_read_b128 v[198:201], v160 offset:18432
	ds_read_b128 v[202:205], v160 offset:19456
	ds_read_b128 v[206:209], v160 offset:20480
	ds_read_b128 v[210:213], v160 offset:21504
	ds_read_b128 v[214:217], v160 offset:22528
	ds_read_b128 v[218:221], v160 offset:23552
	s_waitcnt vmcnt(8)
	s_waitcnt lgkmcnt(0)
	s_setprio 1
	s_barrier
	v_mfma_f32_16x16x32_bf16 v[92:95], v[150:153], v[190:193], v[92:95]
	v_mfma_f32_16x16x32_bf16 v[88:91], v[162:165], v[190:193], v[88:91]
	v_mfma_f32_16x16x32_bf16 v[84:87], v[150:153], v[198:201], v[84:87]
	v_mfma_f32_16x16x32_bf16 v[80:83], v[162:165], v[198:201], v[80:83]
	v_mfma_f32_16x16x32_bf16 v[76:79], v[150:153], v[206:209], v[76:79]
	v_mfma_f32_16x16x32_bf16 v[72:75], v[162:165], v[206:209], v[72:75]
	v_mfma_f32_16x16x32_bf16 v[68:71], v[150:153], v[214:217], v[68:71]
	v_mfma_f32_16x16x32_bf16 v[64:67], v[162:165], v[214:217], v[64:67]
	v_mfma_f32_16x16x32_bf16 v[92:95], v[154:157], v[194:197], v[92:95]
	v_mfma_f32_16x16x32_bf16 v[88:91], v[166:169], v[194:197], v[88:91]
	v_mfma_f32_16x16x32_bf16 v[84:87], v[154:157], v[202:205], v[84:87]
	v_mfma_f32_16x16x32_bf16 v[80:83], v[166:169], v[202:205], v[80:83]
	v_mfma_f32_16x16x32_bf16 v[76:79], v[154:157], v[210:213], v[76:79]
	v_mfma_f32_16x16x32_bf16 v[72:75], v[166:169], v[210:213], v[72:75]
	v_mfma_f32_16x16x32_bf16 v[68:71], v[154:157], v[218:221], v[68:71]
	v_mfma_f32_16x16x32_bf16 v[64:67], v[166:169], v[218:221], v[64:67]
	s_setprio 0
	s_setprio 1
	v_mfma_f32_16x16x32_bf16 v[28:31], v[174:177], v[190:193], v[28:31]
	v_mfma_f32_16x16x32_bf16 v[24:27], v[182:185], v[190:193], v[24:27]
	v_mfma_f32_16x16x32_bf16 v[20:23], v[174:177], v[198:201], v[20:23]
	v_mfma_f32_16x16x32_bf16 v[16:19], v[182:185], v[198:201], v[16:19]
	v_mfma_f32_16x16x32_bf16 v[12:15], v[174:177], v[206:209], v[12:15]
	v_mfma_f32_16x16x32_bf16 v[8:11], v[182:185], v[206:209], v[8:11]
	v_mfma_f32_16x16x32_bf16 v[4:7], v[174:177], v[214:217], v[4:7]
	v_mfma_f32_16x16x32_bf16 v[0:3], v[182:185], v[214:217], v[0:3]
	v_mfma_f32_16x16x32_bf16 v[28:31], v[178:181], v[194:197], v[28:31]
	v_mfma_f32_16x16x32_bf16 v[24:27], v[186:189], v[194:197], v[24:27]
	v_mfma_f32_16x16x32_bf16 v[20:23], v[178:181], v[202:205], v[20:23]
	v_mfma_f32_16x16x32_bf16 v[16:19], v[186:189], v[202:205], v[16:19]
	v_mfma_f32_16x16x32_bf16 v[12:15], v[178:181], v[210:213], v[12:15]
	v_mfma_f32_16x16x32_bf16 v[8:11], v[186:189], v[210:213], v[8:11]
	v_mfma_f32_16x16x32_bf16 v[4:7], v[178:181], v[218:221], v[4:7]
	v_mfma_f32_16x16x32_bf16 v[0:3], v[186:189], v[218:221], v[0:3]
	s_barrier
; #define PG8_STAGE(bufoff, gbase, voff) do { _Pragma("unroll") for (int _i = 0; _i < 2; ++_i) \
;         __builtin_amdgcn_global_load_lds((const unsigned*)((const char*)(gbase) + (voff)[_i]), (PG8_LAS unsigned*)(lds + (bufoff) + ldsw + _i * 8192), 16, 0, 0); } while (0)
; #define PG8_LDA(dst, b, h) do { _Pragma("unroll") for (int m = 0; m < 4; ++m) _Pragma("unroll") for (int k = 0; k < 2; ++k) dst[m][k] = *(const PG8_LAS bf16x8*)(lds + PG8_SA(b, h) + aoff + m * 2048 + k * 1024); } while (0)
; #define PG8_LDB(dst, b, h) do { _Pragma("unroll") for (int n = 0; n < 2; ++n) _Pragma("unroll") for (int k = 0; k < 2; ++k) dst[n][k] = *(const PG8_LAS bf16x8*)(lds + PG8_SB(b, h) + boff + n * 2048 + k * 1024); } while (0)
; #define PG8_MMA(ai, bj, At, Bt) do { __builtin_amdgcn_s_setprio(1); _Pragma("unroll") for (int m = 0; m < 4; ++m) _Pragma("unroll") for (int n = 0; n < 2; ++n) _Pragma("unroll") for (int k = 0; k < 2; ++k) \
;         acc[ai][bj][m][n] = __builtin_amdgcn_mfma_f32_16x16x32_bf16(Bt[n][k], At[m][k], acc[ai][bj][m][n], 0, 0, 0); __builtin_amdgcn_s_setprio(0); } while (0)
; #define PG8_WAIT_V(n) asm volatile("s_waitcnt vmcnt(" #n ")" ::: "memory")
; #define PG8_WAIT_L(n) asm volatile("s_waitcnt lgkmcnt(" #n ")" ::: "memory")
; #define PG8_BAR __builtin_amdgcn_s_barrier()
; #define PG8_SCHED __builtin_amdgcn_sched_barrier(0)
; template <class Epi, class Sched, bool ALIGN_EPI = false, bool SP2 = false>
; __device__ __forceinline__ void gemm_phase(PG8_LAS unsigned char* lds, const Gemm g, const Sched& S, const Epi& E) {
;     ...
;         for (int t = 0; t < nt; t += 2) {
;     ...
;             PG8_LDB(B0, 1, 0); PG8_LDB(B1, 1, 1); PG8_SCHED; PG8_LDA(At, 1, 0); PG8_STAGE(PG8_SA(0, 1), a2 + hstep, voffA);
;             PG8_WAIT_V(8); PG8_WAIT_L(0); PG8_BAR; PG8_MMA(0, 0, At, B0); PG8_MMA(0, 1, At, B1); PG8_BAR; PG8_SCHED;
;             PG8_LDA(At, 1, 1); PG8_STAGE(PG8_SB(1, 0), b3, voffB); PG8_STAGE(PG8_SB(1, 1), b3 + hstep, voffB); PG8_STAGE(PG8_SA(1, 0), a3, voffA);
;             PG8_WAIT_V(8); PG8_WAIT_L(0); PG8_BAR; PG8_MMA(1, 0, At, B0); PG8_MMA(1, 1, At, B1); PG8_BAR; PG8_SCHED;
	s_setprio 0
	s_add_i32 s36, 0, 0x18000
	s_add_i32 s37, 0, 0x1c000
	s_add_u32 s28, s28, 0x160000
	s_addc_u32 s29, s29, 0
	s_mov_b32 m0, s34
	s_nop 0
	global_load_lds_dwordx4 v128, s[28:29]
	s_mov_b32 m0, s35
	s_nop 0
	global_load_lds_dwordx4 v132, s[28:29]
	v_add_u32_e32 v140, s36, v137
	ds_read_b128 v[150:153], v140
	ds_read_b128 v[154:157], v140 offset:1024
	ds_read_b128 v[162:165], v140 offset:2048
	ds_read_b128 v[166:169], v140 offset:3072
	v_add_u32_e32 v140, s37, v137
	ds_read_b128 v[174:177], v140
	ds_read_b128 v[178:181], v140 offset:1024
	ds_read_b128 v[182:185], v140 offset:2048
	ds_read_b128 v[186:189], v140 offset:3072
	ds_read_b128 v[190:193], v160 offset:32768
	ds_read_b128 v[194:197], v160 offset:33792
	ds_read_b128 v[198:201], v160 offset:34816
	ds_read_b128 v[202:205], v160 offset:35840
	ds_read_b128 v[206:209], v160 offset:36864
	ds_read_b128 v[210:213], v160 offset:37888
	ds_read_b128 v[214:217], v160 offset:38912
	ds_read_b128 v[218:221], v160 offset:39936
	s_waitcnt vmcnt(8)
	s_waitcnt lgkmcnt(0)
	s_setprio 1
	s_barrier
	v_mfma_f32_16x16x32_bf16 v[124:127], v[150:153], v[190:193], v[124:127]
	v_mfma_f32_16x16x32_bf16 v[120:123], v[162:165], v[190:193], v[120:123]
	v_mfma_f32_16x16x32_bf16 v[116:119], v[150:153], v[198:201], v[116:119]
	v_mfma_f32_16x16x32_bf16 v[112:115], v[162:165], v[198:201], v[112:115]
	v_mfma_f32_16x16x32_bf16 v[108:111], v[150:153], v[206:209], v[108:111]
	v_mfma_f32_16x16x32_bf16 v[104:107], v[162:165], v[206:209], v[104:107]
	v_mfma_f32_16x16x32_bf16 v[100:103], v[150:153], v[214:217], v[100:103]
	v_mfma_f32_16x16x32_bf16 v[96:99], v[162:165], v[214:217], v[96:99]
	v_mfma_f32_16x16x32_bf16 v[124:127], v[154:157], v[194:197], v[124:127]
	v_mfma_f32_16x16x32_bf16 v[120:123], v[166:169], v[194:197], v[120:123]
	v_mfma_f32_16x16x32_bf16 v[116:119], v[154:157], v[202:205], v[116:119]
	v_mfma_f32_16x16x32_bf16 v[112:115], v[166:169], v[202:205], v[112:115]
	v_mfma_f32_16x16x32_bf16 v[108:111], v[154:157], v[210:213], v[108:111]
	v_mfma_f32_16x16x32_bf16 v[104:107], v[166:169], v[210:213], v[104:107]
	v_mfma_f32_16x16x32_bf16 v[100:103], v[154:157], v[218:221], v[100:103]
	v_mfma_f32_16x16x32_bf16 v[96:99], v[166:169], v[218:221], v[96:99]
	s_setprio 0
	s_setprio 1
	v_mfma_f32_16x16x32_bf16 v[60:63], v[174:177], v[190:193], v[60:63]
	v_mfma_f32_16x16x32_bf16 v[56:59], v[182:185], v[190:193], v[56:59]
	v_mfma_f32_16x16x32_bf16 v[52:55], v[174:177], v[198:201], v[52:55]
	v_mfma_f32_16x16x32_bf16 v[48:51], v[182:185], v[198:201], v[48:51]
	v_mfma_f32_16x16x32_bf16 v[44:47], v[174:177], v[206:209], v[44:47]
	v_mfma_f32_16x16x32_bf16 v[40:43], v[182:185], v[206:209], v[40:43]
	v_mfma_f32_16x16x32_bf16 v[36:39], v[174:177], v[214:217], v[36:39]
	v_mfma_f32_16x16x32_bf16 v[32:35], v[182:185], v[214:217], v[32:35]
	v_mfma_f32_16x16x32_bf16 v[60:63], v[178:181], v[194:197], v[60:63]
	v_mfma_f32_16x16x32_bf16 v[56:59], v[186:189], v[194:197], v[56:59]
	v_mfma_f32_16x16x32_bf16 v[52:55], v[178:181], v[202:205], v[52:55]
	v_mfma_f32_16x16x32_bf16 v[48:51], v[186:189], v[202:205], v[48:51]
	v_mfma_f32_16x16x32_bf16 v[44:47], v[178:181], v[210:213], v[44:47]
	v_mfma_f32_16x16x32_bf16 v[40:43], v[186:189], v[210:213], v[40:43]
	v_mfma_f32_16x16x32_bf16 v[36:39], v[178:181], v[218:221], v[36:39]
	v_mfma_f32_16x16x32_bf16 v[32:35], v[186:189], v[218:221], v[32:35]
	s_barrier
	s_setprio 0
	s_add_i32 s28, s36, s21
	s_add_i32 m0, s28, 0xffffff80
	s_nop 0
	global_load_lds_dwordx4 v130, s[26:27] offset:128
	s_add_i32 m0, s28, 0x1f80
	s_nop 0
	global_load_lds_dwordx4 v134, s[26:27] offset:128
	s_add_u32 s26, s26, 0x160080
	s_addc_u32 s27, s27, 0
	s_add_i32 s28, s37, s21
	s_mov_b32 m0, s28
	s_nop 0
	global_load_lds_dwordx4 v130, s[26:27]
	s_add_i32 m0, s28, 0x2000
	s_nop 0
	global_load_lds_dwordx4 v134, s[26:27]
	v_lshl_add_u64 v[222:223], v[226:227], 0, s[16:17]
	s_mov_b32 m0, s48
	s_nop 0
	global_load_lds_dwordx4 v[222:223], off
	v_lshl_add_u64 v[222:223], v[228:229], 0, s[16:17]
	s_mov_b32 m0, s49
	s_nop 0
	global_load_lds_dwordx4 v[222:223], off
	ds_read_b128 v[190:193], v160 offset:49152
	ds_read_b128 v[194:197], v160 offset:50176
	ds_read_b128 v[198:201], v160 offset:51200
	ds_read_b128 v[202:205], v160 offset:52224
	ds_read_b128 v[206:209], v160 offset:53248
	ds_read_b128 v[210:213], v160 offset:54272
	ds_read_b128 v[214:217], v160 offset:55296
	ds_read_b128 v[218:221], v160 offset:56320
	s_waitcnt vmcnt(8)
	s_waitcnt lgkmcnt(0)
	s_setprio 1
	s_barrier
	v_mfma_f32_16x16x32_bf16 v[92:95], v[150:153], v[190:193], v[92:95]
	v_mfma_f32_16x16x32_bf16 v[88:91], v[162:165], v[190:193], v[88:91]
	v_mfma_f32_16x16x32_bf16 v[84:87], v[150:153], v[198:201], v[84:87]
	v_mfma_f32_16x16x32_bf16 v[80:83], v[162:165], v[198:201], v[80:83]
	v_mfma_f32_16x16x32_bf16 v[76:79], v[150:153], v[206:209], v[76:79]
	v_mfma_f32_16x16x32_bf16 v[72:75], v[162:165], v[206:209], v[72:75]
	v_mfma_f32_16x16x32_bf16 v[68:71], v[150:153], v[214:217], v[68:71]
	v_mfma_f32_16x16x32_bf16 v[64:67], v[162:165], v[214:217], v[64:67]
	v_mfma_f32_16x16x32_bf16 v[92:95], v[154:157], v[194:197], v[92:95]
	v_mfma_f32_16x16x32_bf16 v[88:91], v[166:169], v[194:197], v[88:91]
	v_mfma_f32_16x16x32_bf16 v[84:87], v[154:157], v[202:205], v[84:87]
	v_mfma_f32_16x16x32_bf16 v[80:83], v[166:169], v[202:205], v[80:83]
	v_mfma_f32_16x16x32_bf16 v[76:79], v[154:157], v[210:213], v[76:79]
	v_mfma_f32_16x16x32_bf16 v[72:75], v[166:169], v[210:213], v[72:75]
	v_mfma_f32_16x16x32_bf16 v[68:71], v[154:157], v[218:221], v[68:71]
	v_mfma_f32_16x16x32_bf16 v[64:67], v[166:169], v[218:221], v[64:67]
	s_setprio 0
	s_setprio 1
	v_mfma_f32_16x16x32_bf16 v[28:31], v[174:177], v[190:193], v[28:31]
	v_mfma_f32_16x16x32_bf16 v[24:27], v[182:185], v[190:193], v[24:27]
	v_mfma_f32_16x16x32_bf16 v[20:23], v[174:177], v[198:201], v[20:23]
	v_mfma_f32_16x16x32_bf16 v[16:19], v[182:185], v[198:201], v[16:19]
	v_mfma_f32_16x16x32_bf16 v[12:15], v[174:177], v[206:209], v[12:15]
	v_mfma_f32_16x16x32_bf16 v[8:11], v[182:185], v[206:209], v[8:11]
	v_mfma_f32_16x16x32_bf16 v[4:7], v[174:177], v[214:217], v[4:7]
	v_mfma_f32_16x16x32_bf16 v[0:3], v[182:185], v[214:217], v[0:3]
	v_mfma_f32_16x16x32_bf16 v[28:31], v[178:181], v[194:197], v[28:31]
	v_mfma_f32_16x16x32_bf16 v[24:27], v[186:189], v[194:197], v[24:27]
	v_mfma_f32_16x16x32_bf16 v[20:23], v[178:181], v[202:205], v[20:23]
	v_mfma_f32_16x16x32_bf16 v[16:19], v[186:189], v[202:205], v[16:19]
	v_mfma_f32_16x16x32_bf16 v[12:15], v[178:181], v[210:213], v[12:15]
	v_mfma_f32_16x16x32_bf16 v[8:11], v[186:189], v[210:213], v[8:11]
	v_mfma_f32_16x16x32_bf16 v[4:7], v[178:181], v[218:221], v[4:7]
	v_mfma_f32_16x16x32_bf16 v[0:3], v[186:189], v[218:221], v[0:3]
	s_barrier
	s_setprio 0
	s_add_i32 s73, s73, 2
	s_add_u32 s24, s24, 0x100
	s_addc_u32 s25, s25, 0
	s_add_u32 s67, s67, 0x100
	s_addc_u32 s72, s72, 0
	s_cmpk_gt_u32 s73, 0x55
	s_cbranch_scc0 .LBB0_606
	s_and_b64 vcc, exec, s[18:19]
	s_cbranch_vccz .LBB0_609
	s_barrier

; #define PG8_STAGE(bufoff, gbase, voff) do { _Pragma("unroll") for (int _i = 0; _i < 2; ++_i) \
;         __builtin_amdgcn_global_load_lds((const unsigned*)((const char*)(gbase) + (voff)[_i]), (PG8_LAS unsigned*)(lds + (bufoff) + ldsw + _i * 8192), 16, 0, 0); } while (0)
; #define PG8_LDA(dst, b, h) do { _Pragma("unroll") for (int m = 0; m < 4; ++m) _Pragma("unroll") for (int k = 0; k < 2; ++k) dst[m][k] = *(const PG8_LAS bf16x8*)(lds + PG8_SA(b, h) + aoff + m * 2048 + k * 1024); } while (0)
; #define PG8_LDB(dst, b, h) do { _Pragma("unroll") for (int n = 0; n < 2; ++n) _Pragma("unroll") for (int k = 0; k < 2; ++k) dst[n][k] = *(const PG8_LAS bf16x8*)(lds + PG8_SB(b, h) + boff + n * 2048 + k * 1024); } while (0)
; #define PG8_MMA(ai, bj, At, Bt) do { __builtin_amdgcn_s_setprio(1); _Pragma("unroll") for (int m = 0; m < 4; ++m) _Pragma("unroll") for (int n = 0; n < 2; ++n) _Pragma("unroll") for (int k = 0; k < 2; ++k) \
;         acc[ai][bj][m][n] = __builtin_amdgcn_mfma_f32_16x16x32_bf16(Bt[n][k], At[m][k], acc[ai][bj][m][n], 0, 0, 0); __builtin_amdgcn_s_setprio(0); } while (0)
; #define PG8_WAIT_V(n) asm volatile("s_waitcnt vmcnt(" #n ")" ::: "memory")
; #define PG8_WAIT_L(n) asm volatile("s_waitcnt lgkmcnt(" #n ")" ::: "memory")
; #define PG8_BAR __builtin_amdgcn_s_barrier()
; #define PG8_SCHED __builtin_amdgcn_sched_barrier(0)
; template <class Epi, class Sched, bool ALIGN_EPI = false, bool SP2 = false>
; __device__ __forceinline__ void gemm_phase(PG8_LAS unsigned char* lds, const Gemm g, const Sched& S, const Epi& E) {
;     ...
;             PG8_LDB(B0, 0, 0); PG8_LDB(B1, 0, 1); PG8_SCHED; PG8_LDA(At, 0, 0); PG8_STAGE(PG8_SA(1, 1), a1 + hstep, voffA);
;             PG8_WAIT_V(8); PG8_WAIT_L(0); PG8_BAR; PG8_MMA(0, 0, At, B0); PG8_MMA(0, 1, At, B1); PG8_BAR; PG8_SCHED;
;             PG8_LDA(At, 0, 1); PG8_STAGE(PG8_SB(0, 0), b2, voffB); PG8_STAGE(PG8_SB(0, 1), b2 + hstep, voffB); PG8_STAGE(PG8_SA(0, 0), a2, voffA);
;             PG8_WAIT_V(8); PG8_WAIT_L(0); PG8_BAR; PG8_MMA(1, 0, At, B0); PG8_MMA(1, 1, At, B1); PG8_BAR; PG8_SCHED;
.LBB0_744:
	s_add_u32 s36, s34, 0xfff80080
	s_addc_u32 s37, s35, -1
	s_cmp_eq_u32 s75, 28
	s_cselect_b32 s51, s25, s37
	s_cselect_b32 s50, s71, s36
	s_cselect_b32 s49, s23, s74
	s_cselect_b32 s48, s72, s73
	s_add_i32 m0, s31, 0xc000
	s_nop 0
	global_load_lds_dwordx4 v150, s[34:35]
	s_add_i32 m0, s31, 0xe000
	s_nop 0
	global_load_lds_dwordx4 v152, s[34:35]
	ds_read_b128 v[112:115], v174
	ds_read_b128 v[116:119], v174 offset:1024
	ds_read_b128 v[158:161], v174 offset:2048
	ds_read_b128 v[162:165], v174 offset:3072
	ds_read_b128 v[166:169], v175
	ds_read_b128 v[178:181], v175 offset:1024
	ds_read_b128 v[182:185], v175 offset:2048
	ds_read_b128 v[186:189], v175 offset:3072
	ds_read_b128 v[190:193], v176
	ds_read_b128 v[194:197], v176 offset:1024
	ds_read_b128 v[198:201], v176 offset:2048
	ds_read_b128 v[202:205], v176 offset:3072
	ds_read_b128 v[206:209], v176 offset:4096
	ds_read_b128 v[210:213], v176 offset:5120
	ds_read_b128 v[214:217], v176 offset:6144
	ds_read_b128 v[218:221], v176 offset:7168
	s_waitcnt vmcnt(8)
	s_waitcnt lgkmcnt(0)
	s_setprio 1
	s_barrier
	v_mfma_f32_16x16x32_bf16 v[132:135], v[112:115], v[190:193], v[132:135]
	v_mfma_f32_16x16x32_bf16 v[128:131], v[158:161], v[190:193], v[128:131]
	v_mfma_f32_16x16x32_bf16 v[124:127], v[112:115], v[198:201], v[124:127]
	v_mfma_f32_16x16x32_bf16 v[120:123], v[158:161], v[198:201], v[120:123]
	v_mfma_f32_16x16x32_bf16 v[108:111], v[112:115], v[206:209], v[108:111]
	v_mfma_f32_16x16x32_bf16 v[104:107], v[158:161], v[206:209], v[104:107]
	v_mfma_f32_16x16x32_bf16 v[100:103], v[112:115], v[214:217], v[100:103]
	v_mfma_f32_16x16x32_bf16 v[96:99], v[158:161], v[214:217], v[96:99]
	v_mfma_f32_16x16x32_bf16 v[132:135], v[116:119], v[194:197], v[132:135]
	v_mfma_f32_16x16x32_bf16 v[128:131], v[162:165], v[194:197], v[128:131]
	v_mfma_f32_16x16x32_bf16 v[124:127], v[116:119], v[202:205], v[124:127]
	v_mfma_f32_16x16x32_bf16 v[120:123], v[162:165], v[202:205], v[120:123]
	v_mfma_f32_16x16x32_bf16 v[108:111], v[116:119], v[210:213], v[108:111]
	v_mfma_f32_16x16x32_bf16 v[104:107], v[162:165], v[210:213], v[104:107]
	v_mfma_f32_16x16x32_bf16 v[100:103], v[116:119], v[218:221], v[100:103]
	v_mfma_f32_16x16x32_bf16 v[96:99], v[162:165], v[218:221], v[96:99]
	s_setprio 0
	s_setprio 1
	v_mfma_f32_16x16x32_bf16 v[60:63], v[166:169], v[190:193], v[60:63]
	v_mfma_f32_16x16x32_bf16 v[56:59], v[182:185], v[190:193], v[56:59]
	v_mfma_f32_16x16x32_bf16 v[52:55], v[166:169], v[198:201], v[52:55]
	v_mfma_f32_16x16x32_bf16 v[48:51], v[182:185], v[198:201], v[48:51]
	v_mfma_f32_16x16x32_bf16 v[44:47], v[166:169], v[206:209], v[44:47]
	v_mfma_f32_16x16x32_bf16 v[40:43], v[182:185], v[206:209], v[40:43]
	v_mfma_f32_16x16x32_bf16 v[36:39], v[166:169], v[214:217], v[36:39]
	v_mfma_f32_16x16x32_bf16 v[32:35], v[182:185], v[214:217], v[32:35]
	v_mfma_f32_16x16x32_bf16 v[60:63], v[178:181], v[194:197], v[60:63]
	v_mfma_f32_16x16x32_bf16 v[56:59], v[186:189], v[194:197], v[56:59]
	v_mfma_f32_16x16x32_bf16 v[52:55], v[178:181], v[202:205], v[52:55]
	v_mfma_f32_16x16x32_bf16 v[48:51], v[186:189], v[202:205], v[48:51]
	v_mfma_f32_16x16x32_bf16 v[44:47], v[178:181], v[210:213], v[44:47]
	v_mfma_f32_16x16x32_bf16 v[40:43], v[186:189], v[210:213], v[40:43]
	v_mfma_f32_16x16x32_bf16 v[36:39], v[178:181], v[218:221], v[36:39]
	v_mfma_f32_16x16x32_bf16 v[32:35], v[186:189], v[218:221], v[32:35]
	s_barrier
	s_setprio 0
	s_add_i32 s36, s66, s21
	s_mov_b32 m0, s36
	s_nop 0
	global_load_lds_dwordx4 v142, s[48:49]
	s_add_i32 m0, s36, 0x2000
	s_add_u32 s36, s48, 0x80000
	s_addc_u32 s37, s49, 0
	s_add_i32 s58, s67, s21
	global_load_lds_dwordx4 v146, s[48:49]
	s_mov_b32 m0, s58
	s_nop 0
	global_load_lds_dwordx4 v142, s[36:37]
	s_add_i32 m0, s58, 0x2000
	s_nop 0
	global_load_lds_dwordx4 v146, s[36:37]
	s_mov_b32 m0, s31
	s_nop 0
	global_load_lds_dwordx4 v140, s[50:51]
	s_mov_b32 m0, s39
	s_nop 0
	global_load_lds_dwordx4 v144, s[50:51]
	ds_read_b128 v[190:193], v176 offset:16384
	ds_read_b128 v[194:197], v176 offset:17408
	ds_read_b128 v[198:201], v176 offset:18432
	ds_read_b128 v[202:205], v176 offset:19456
	ds_read_b128 v[206:209], v176 offset:20480
	ds_read_b128 v[210:213], v176 offset:21504
	ds_read_b128 v[214:217], v176 offset:22528
	ds_read_b128 v[218:221], v176 offset:23552
	s_waitcnt vmcnt(8)
	s_waitcnt lgkmcnt(0)
	s_setprio 1
	s_barrier
	v_mfma_f32_16x16x32_bf16 v[92:95], v[112:115], v[190:193], v[92:95]
	v_mfma_f32_16x16x32_bf16 v[88:91], v[158:161], v[190:193], v[88:91]
	v_mfma_f32_16x16x32_bf16 v[84:87], v[112:115], v[198:201], v[84:87]
	v_mfma_f32_16x16x32_bf16 v[80:83], v[158:161], v[198:201], v[80:83]
	v_mfma_f32_16x16x32_bf16 v[76:79], v[112:115], v[206:209], v[76:79]
	v_mfma_f32_16x16x32_bf16 v[72:75], v[158:161], v[206:209], v[72:75]
	v_mfma_f32_16x16x32_bf16 v[68:71], v[112:115], v[214:217], v[68:71]
	v_mfma_f32_16x16x32_bf16 v[64:67], v[158:161], v[214:217], v[64:67]
	v_mfma_f32_16x16x32_bf16 v[92:95], v[116:119], v[194:197], v[92:95]
	v_mfma_f32_16x16x32_bf16 v[88:91], v[162:165], v[194:197], v[88:91]
	v_mfma_f32_16x16x32_bf16 v[84:87], v[116:119], v[202:205], v[84:87]
	v_mfma_f32_16x16x32_bf16 v[80:83], v[162:165], v[202:205], v[80:83]
	v_mfma_f32_16x16x32_bf16 v[76:79], v[116:119], v[210:213], v[76:79]
	v_mfma_f32_16x16x32_bf16 v[72:75], v[162:165], v[210:213], v[72:75]
	v_mfma_f32_16x16x32_bf16 v[68:71], v[116:119], v[218:221], v[68:71]
	v_mfma_f32_16x16x32_bf16 v[64:67], v[162:165], v[218:221], v[64:67]
	s_setprio 0
	s_setprio 1
	v_mfma_f32_16x16x32_bf16 v[28:31], v[166:169], v[190:193], v[28:31]
	v_mfma_f32_16x16x32_bf16 v[24:27], v[182:185], v[190:193], v[24:27]
	v_mfma_f32_16x16x32_bf16 v[20:23], v[166:169], v[198:201], v[20:23]
	v_mfma_f32_16x16x32_bf16 v[16:19], v[182:185], v[198:201], v[16:19]
	v_mfma_f32_16x16x32_bf16 v[12:15], v[166:169], v[206:209], v[12:15]
	v_mfma_f32_16x16x32_bf16 v[8:11], v[182:185], v[206:209], v[8:11]
	v_mfma_f32_16x16x32_bf16 v[4:7], v[166:169], v[214:217], v[4:7]
	v_mfma_f32_16x16x32_bf16 v[0:3], v[182:185], v[214:217], v[0:3]
	v_mfma_f32_16x16x32_bf16 v[28:31], v[178:181], v[194:197], v[28:31]
	v_mfma_f32_16x16x32_bf16 v[24:27], v[186:189], v[194:197], v[24:27]
	v_mfma_f32_16x16x32_bf16 v[20:23], v[178:181], v[202:205], v[20:23]
	v_mfma_f32_16x16x32_bf16 v[16:19], v[186:189], v[202:205], v[16:19]
	v_mfma_f32_16x16x32_bf16 v[12:15], v[178:181], v[210:213], v[12:15]
	v_mfma_f32_16x16x32_bf16 v[8:11], v[186:189], v[210:213], v[8:11]
	v_mfma_f32_16x16x32_bf16 v[4:7], v[178:181], v[218:221], v[4:7]
	v_mfma_f32_16x16x32_bf16 v[0:3], v[186:189], v[218:221], v[0:3]
	s_barrier
; #define PG8_STAGE(bufoff, gbase, voff) do { _Pragma("unroll") for (int _i = 0; _i < 2; ++_i) \
;         __builtin_amdgcn_global_load_lds((const unsigned*)((const char*)(gbase) + (voff)[_i]), (PG8_LAS unsigned*)(lds + (bufoff) + ldsw + _i * 8192), 16, 0, 0); } while (0)
; #define PG8_LDA(dst, b, h) do { _Pragma("unroll") for (int m = 0; m < 4; ++m) _Pragma("unroll") for (int k = 0; k < 2; ++k) dst[m][k] = *(const PG8_LAS bf16x8*)(lds + PG8_SA(b, h) + aoff + m * 2048 + k * 1024); } while (0)
; #define PG8_LDB(dst, b, h) do { _Pragma("unroll") for (int n = 0; n < 2; ++n) _Pragma("unroll") for (int k = 0; k < 2; ++k) dst[n][k] = *(const PG8_LAS bf16x8*)(lds + PG8_SB(b, h) + boff + n * 2048 + k * 1024); } while (0)
; #define PG8_MMA(ai, bj, At, Bt) do { __builtin_amdgcn_s_setprio(1); _Pragma("unroll") for (int m = 0; m < 4; ++m) _Pragma("unroll") for (int n = 0; n < 2; ++n) _Pragma("unroll") for (int k = 0; k < 2; ++k) \
;         acc[ai][bj][m][n] = __builtin_amdgcn_mfma_f32_16x16x32_bf16(Bt[n][k], At[m][k], acc[ai][bj][m][n], 0, 0, 0); __builtin_amdgcn_s_setprio(0); } while (0)
; #define PG8_WAIT_V(n) asm volatile("s_waitcnt vmcnt(" #n ")" ::: "memory")
; #define PG8_WAIT_L(n) asm volatile("s_waitcnt lgkmcnt(" #n ")" ::: "memory")
; #define PG8_BAR __builtin_amdgcn_s_barrier()
; #define PG8_SCHED __builtin_amdgcn_sched_barrier(0)
; template <class Epi, class Sched, bool ALIGN_EPI = false, bool SP2 = false>
; __device__ __forceinline__ void gemm_phase(PG8_LAS unsigned char* lds, const Gemm g, const Sched& S, const Epi& E) {
;     ...
;         for (int t = 0; t < nt; t += 2) {
;     ...
;             PG8_LDB(B0, 1, 0); PG8_LDB(B1, 1, 1); PG8_SCHED; PG8_LDA(At, 1, 0); PG8_STAGE(PG8_SA(0, 1), a2 + hstep, voffA);
;             PG8_WAIT_V(8); PG8_WAIT_L(0); PG8_BAR; PG8_MMA(0, 0, At, B0); PG8_MMA(0, 1, At, B1); PG8_BAR; PG8_SCHED;
;             PG8_LDA(At, 1, 1); PG8_STAGE(PG8_SB(1, 0), b3, voffB); PG8_STAGE(PG8_SB(1, 1), b3 + hstep, voffB); PG8_STAGE(PG8_SA(1, 0), a3, voffA);
;             PG8_WAIT_V(8); PG8_WAIT_L(0); PG8_BAR; PG8_MMA(1, 0, At, B0); PG8_MMA(1, 1, At, B1); PG8_BAR; PG8_SCHED;
	s_setprio 0
	s_add_i32 s58, 0, 0x18000
	s_add_i32 s59, 0, 0x1c000
	s_add_u32 s36, s50, 0x80000
	s_addc_u32 s37, s51, 0
	s_mov_b32 m0, s52
	s_nop 0
	global_load_lds_dwordx4 v140, s[36:37]
	s_mov_b32 m0, s53
	s_nop 0
	global_load_lds_dwordx4 v144, s[36:37]
	v_add_u32_e32 v148, s58, v137
	ds_read_b128 v[112:115], v148
	ds_read_b128 v[116:119], v148 offset:1024
	ds_read_b128 v[158:161], v148 offset:2048
	ds_read_b128 v[162:165], v148 offset:3072
	v_add_u32_e32 v148, s59, v137
	ds_read_b128 v[166:169], v148
	ds_read_b128 v[178:181], v148 offset:1024
	ds_read_b128 v[182:185], v148 offset:2048
	ds_read_b128 v[186:189], v148 offset:3072
	ds_read_b128 v[190:193], v176 offset:32768
	ds_read_b128 v[194:197], v176 offset:33792
	ds_read_b128 v[198:201], v176 offset:34816
	ds_read_b128 v[202:205], v176 offset:35840
	ds_read_b128 v[206:209], v176 offset:36864
	ds_read_b128 v[210:213], v176 offset:37888
	ds_read_b128 v[214:217], v176 offset:38912
	ds_read_b128 v[218:221], v176 offset:39936
	s_waitcnt vmcnt(8)
	s_waitcnt lgkmcnt(0)
	s_setprio 1
	s_barrier
	v_mfma_f32_16x16x32_bf16 v[132:135], v[112:115], v[190:193], v[132:135]
	v_mfma_f32_16x16x32_bf16 v[128:131], v[158:161], v[190:193], v[128:131]
	v_mfma_f32_16x16x32_bf16 v[124:127], v[112:115], v[198:201], v[124:127]
	v_mfma_f32_16x16x32_bf16 v[120:123], v[158:161], v[198:201], v[120:123]
	v_mfma_f32_16x16x32_bf16 v[108:111], v[112:115], v[206:209], v[108:111]
	v_mfma_f32_16x16x32_bf16 v[104:107], v[158:161], v[206:209], v[104:107]
	v_mfma_f32_16x16x32_bf16 v[100:103], v[112:115], v[214:217], v[100:103]
	v_mfma_f32_16x16x32_bf16 v[96:99], v[158:161], v[214:217], v[96:99]
	v_mfma_f32_16x16x32_bf16 v[132:135], v[116:119], v[194:197], v[132:135]
	v_mfma_f32_16x16x32_bf16 v[128:131], v[162:165], v[194:197], v[128:131]
	v_mfma_f32_16x16x32_bf16 v[124:127], v[116:119], v[202:205], v[124:127]
	v_mfma_f32_16x16x32_bf16 v[120:123], v[162:165], v[202:205], v[120:123]
	v_mfma_f32_16x16x32_bf16 v[108:111], v[116:119], v[210:213], v[108:111]
	v_mfma_f32_16x16x32_bf16 v[104:107], v[162:165], v[210:213], v[104:107]
	v_mfma_f32_16x16x32_bf16 v[100:103], v[116:119], v[218:221], v[100:103]
	v_mfma_f32_16x16x32_bf16 v[96:99], v[162:165], v[218:221], v[96:99]
	s_setprio 0
	s_setprio 1
	v_mfma_f32_16x16x32_bf16 v[60:63], v[166:169], v[190:193], v[60:63]
	v_mfma_f32_16x16x32_bf16 v[56:59], v[182:185], v[190:193], v[56:59]
	v_mfma_f32_16x16x32_bf16 v[52:55], v[166:169], v[198:201], v[52:55]
	v_mfma_f32_16x16x32_bf16 v[48:51], v[182:185], v[198:201], v[48:51]
	v_mfma_f32_16x16x32_bf16 v[44:47], v[166:169], v[206:209], v[44:47]
	v_mfma_f32_16x16x32_bf16 v[40:43], v[182:185], v[206:209], v[40:43]
	v_mfma_f32_16x16x32_bf16 v[36:39], v[166:169], v[214:217], v[36:39]
	v_mfma_f32_16x16x32_bf16 v[32:35], v[182:185], v[214:217], v[32:35]
	v_mfma_f32_16x16x32_bf16 v[60:63], v[178:181], v[194:197], v[60:63]
	v_mfma_f32_16x16x32_bf16 v[56:59], v[186:189], v[194:197], v[56:59]
	v_mfma_f32_16x16x32_bf16 v[52:55], v[178:181], v[202:205], v[52:55]
	v_mfma_f32_16x16x32_bf16 v[48:51], v[186:189], v[202:205], v[48:51]
	v_mfma_f32_16x16x32_bf16 v[44:47], v[178:181], v[210:213], v[44:47]
	v_mfma_f32_16x16x32_bf16 v[40:43], v[186:189], v[210:213], v[40:43]
	v_mfma_f32_16x16x32_bf16 v[36:39], v[178:181], v[218:221], v[36:39]
	v_mfma_f32_16x16x32_bf16 v[32:35], v[186:189], v[218:221], v[32:35]
	s_barrier
	s_setprio 0
	s_add_i32 s36, s58, s21
	s_add_i32 m0, s36, 0xffffff80
	s_nop 0
	global_load_lds_dwordx4 v142, s[48:49] offset:128
	s_add_i32 m0, s36, 0x1f80
	s_nop 0
	global_load_lds_dwordx4 v146, s[48:49] offset:128
	s_add_u32 s36, s48, 0x80080
	s_addc_u32 s37, s49, 0
	s_add_i32 s48, s59, s21
	s_mov_b32 m0, s48
	s_nop 0
	global_load_lds_dwordx4 v142, s[36:37]
	s_add_i32 m0, s48, 0x2000
	s_nop 0
	global_load_lds_dwordx4 v146, s[36:37]
	s_add_i32 m0, s55, 0xffffff80
	s_nop 0
	global_load_lds_dwordx4 v140, s[50:51] offset:128
	s_add_i32 m0, s57, 0xffffff80
	s_nop 0
	global_load_lds_dwordx4 v144, s[50:51] offset:128
	ds_read_b128 v[190:193], v176 offset:49152
	ds_read_b128 v[194:197], v176 offset:50176
	ds_read_b128 v[198:201], v176 offset:51200
	ds_read_b128 v[202:205], v176 offset:52224
	ds_read_b128 v[206:209], v176 offset:53248
	ds_read_b128 v[210:213], v176 offset:54272
	ds_read_b128 v[214:217], v176 offset:55296
	ds_read_b128 v[218:221], v176 offset:56320
	s_waitcnt vmcnt(8)
	s_waitcnt lgkmcnt(0)
	s_setprio 1
	s_barrier
	v_mfma_f32_16x16x32_bf16 v[92:95], v[112:115], v[190:193], v[92:95]
	v_mfma_f32_16x16x32_bf16 v[88:91], v[158:161], v[190:193], v[88:91]
	v_mfma_f32_16x16x32_bf16 v[84:87], v[112:115], v[198:201], v[84:87]
	v_mfma_f32_16x16x32_bf16 v[80:83], v[158:161], v[198:201], v[80:83]
	v_mfma_f32_16x16x32_bf16 v[76:79], v[112:115], v[206:209], v[76:79]
	v_mfma_f32_16x16x32_bf16 v[72:75], v[158:161], v[206:209], v[72:75]
	v_mfma_f32_16x16x32_bf16 v[68:71], v[112:115], v[214:217], v[68:71]
	v_mfma_f32_16x16x32_bf16 v[64:67], v[158:161], v[214:217], v[64:67]
	v_mfma_f32_16x16x32_bf16 v[92:95], v[116:119], v[194:197], v[92:95]
	v_mfma_f32_16x16x32_bf16 v[88:91], v[162:165], v[194:197], v[88:91]
	v_mfma_f32_16x16x32_bf16 v[84:87], v[116:119], v[202:205], v[84:87]
	v_mfma_f32_16x16x32_bf16 v[80:83], v[162:165], v[202:205], v[80:83]
	v_mfma_f32_16x16x32_bf16 v[76:79], v[116:119], v[210:213], v[76:79]
	v_mfma_f32_16x16x32_bf16 v[72:75], v[162:165], v[210:213], v[72:75]
	v_mfma_f32_16x16x32_bf16 v[68:71], v[116:119], v[218:221], v[68:71]
	v_mfma_f32_16x16x32_bf16 v[64:67], v[162:165], v[218:221], v[64:67]
	s_setprio 0
	s_setprio 1
	v_mfma_f32_16x16x32_bf16 v[28:31], v[166:169], v[190:193], v[28:31]
	v_mfma_f32_16x16x32_bf16 v[24:27], v[182:185], v[190:193], v[24:27]
	v_mfma_f32_16x16x32_bf16 v[20:23], v[166:169], v[198:201], v[20:23]
	v_mfma_f32_16x16x32_bf16 v[16:19], v[182:185], v[198:201], v[16:19]
	v_mfma_f32_16x16x32_bf16 v[12:15], v[166:169], v[206:209], v[12:15]
	v_mfma_f32_16x16x32_bf16 v[8:11], v[182:185], v[206:209], v[8:11]
	v_mfma_f32_16x16x32_bf16 v[4:7], v[166:169], v[214:217], v[4:7]
	v_mfma_f32_16x16x32_bf16 v[0:3], v[182:185], v[214:217], v[0:3]
	v_mfma_f32_16x16x32_bf16 v[28:31], v[178:181], v[194:197], v[28:31]
	v_mfma_f32_16x16x32_bf16 v[24:27], v[186:189], v[194:197], v[24:27]
	v_mfma_f32_16x16x32_bf16 v[20:23], v[178:181], v[202:205], v[20:23]
	v_mfma_f32_16x16x32_bf16 v[16:19], v[186:189], v[202:205], v[16:19]
	v_mfma_f32_16x16x32_bf16 v[12:15], v[178:181], v[210:213], v[12:15]
	v_mfma_f32_16x16x32_bf16 v[8:11], v[186:189], v[210:213], v[8:11]
	v_mfma_f32_16x16x32_bf16 v[4:7], v[178:181], v[218:221], v[4:7]
	v_mfma_f32_16x16x32_bf16 v[0:3], v[186:189], v[218:221], v[0:3]
	s_barrier
	s_setprio 0
	s_add_i32 s75, s75, 2
	s_add_u32 s34, s34, 0x100
	s_addc_u32 s35, s35, 0
	s_add_u32 s73, s73, 0x100
	s_addc_u32 s74, s74, 0
	s_cmp_gt_u32 s75, 29
	s_cbranch_scc0 .LBB0_744
	s_and_b64 vcc, exec, s[18:19]
	s_cbranch_vccz .LBB0_747
	s_barrier
